# GEMM K-loops: LDS-DMA loads in SGPR-base + VGPR-offset form (no per-piece 64-bit VALU address adds)
# speedup vs baseline: 1.0033x; 1.0033x over previous
; #define PG8_STAGE(bufoff, gbase, voff) do { _Pragma("unroll") for (int _i = 0; _i < 2; ++_i) \
;         __builtin_amdgcn_global_load_lds((const unsigned*)((const char*)(gbase) + (voff)[_i]), (PG8_LAS unsigned*)(lds + (bufoff) + ldsw + _i * 8192), 16, 0, 0); } while (0)
; #define PG8_LDA(dst, b, h) do { _Pragma("unroll") for (int m = 0; m < 4; ++m) _Pragma("unroll") for (int k = 0; k < 2; ++k) dst[m][k] = *(const PG8_LAS bf16x8*)(lds + PG8_SA(b, h) + aoff + m * 2048 + k * 1024); } while (0)
; #define PG8_LDB(dst, b, h) do { _Pragma("unroll") for (int n = 0; n < 2; ++n) _Pragma("unroll") for (int k = 0; k < 2; ++k) dst[n][k] = *(const PG8_LAS bf16x8*)(lds + PG8_SB(b, h) + boff + n * 2048 + k * 1024); } while (0)
; #define PG8_MMA(ai, bj, At, Bt) do { __builtin_amdgcn_s_setprio(1); _Pragma("unroll") for (int m = 0; m < 4; ++m) _Pragma("unroll") for (int n = 0; n < 2; ++n) _Pragma("unroll") for (int k = 0; k < 2; ++k) \
;         acc[ai][bj][m][n] = __builtin_amdgcn_mfma_f32_16x16x32_bf16(Bt[n][k], At[m][k], acc[ai][bj][m][n], 0, 0, 0); __builtin_amdgcn_s_setprio(0); } while (0)
; #define PG8_WAIT_V(n) asm volatile("s_waitcnt vmcnt(" #n ")" ::: "memory")
; #define PG8_WAIT_L(n) asm volatile("s_waitcnt lgkmcnt(" #n ")" ::: "memory")
; #define PG8_BAR __builtin_amdgcn_s_barrier()
; #define PG8_SCHED __builtin_amdgcn_sched_barrier(0)
; template <class Epi, class Sched, bool ALIGN_EPI = false, bool SP2 = false>
; __device__ __forceinline__ void gemm_phase(PG8_LAS unsigned char* lds, const Gemm g, const Sched& S, const Epi& E) {
;     ...
;             PG8_LDB(B0, 0, 0); PG8_LDB(B1, 0, 1); PG8_SCHED; PG8_LDA(At, 0, 0); PG8_STAGE(PG8_SA(1, 1), a1 + hstep, voffA);
;             PG8_WAIT_V(8); PG8_WAIT_L(0); PG8_BAR; PG8_MMA(0, 0, At, B0); PG8_MMA(0, 1, At, B1); PG8_BAR; PG8_SCHED;
;             PG8_LDA(At, 0, 1); PG8_STAGE(PG8_SB(0, 0), b2, voffB); PG8_STAGE(PG8_SB(0, 1), b2 + hstep, voffB); PG8_STAGE(PG8_SA(0, 0), a2, voffA);
;             PG8_WAIT_V(8); PG8_WAIT_L(0); PG8_BAR; PG8_MMA(1, 0, At, B0); PG8_MMA(1, 1, At, B1); PG8_BAR; PG8_SCHED;
.LBB0_139:
	ds_read_b128 v[144:147], v160
	ds_read_b128 v[164:167], v160 offset:1024
	ds_read_b128 v[172:175], v160 offset:2048
	ds_read_b128 v[176:179], v160 offset:3072
	ds_read_b128 v[180:183], v161
	ds_read_b128 v[184:187], v161 offset:1024
	ds_read_b128 v[188:191], v161 offset:2048
	ds_read_b128 v[192:195], v161 offset:3072
	s_add_u32 s34, s30, 0xfff80080
	s_addc_u32 s35, s31, -1
	s_cmp_eq_u32 s84, 28
	s_cselect_b32 s49, s23, s35
	s_cselect_b32 s48, s80, s34
	s_cselect_b32 s35, s21, s83
	s_cselect_b32 s34, s81, s82
	s_add_i32 m0, s29, 0xc000
	ds_read_b128 v[196:199], v162
	ds_read_b128 v[200:203], v162 offset:1024
	ds_read_b128 v[204:207], v162 offset:2048
	ds_read_b128 v[208:211], v162 offset:3072
	ds_read_b128 v[212:215], v162 offset:4096
	ds_read_b128 v[216:219], v162 offset:5120
	ds_read_b128 v[220:223], v162 offset:6144
	ds_read_b128 v[224:227], v162 offset:7168
	global_load_lds_dwordx4 v136, s[30:31]
	s_add_i32 m0, s29, 0xe000
	s_nop 0
	global_load_lds_dwordx4 v138, s[30:31]
	s_waitcnt vmcnt(8)
	s_waitcnt lgkmcnt(0)
	s_barrier
	s_setprio 1
	s_waitcnt lgkmcnt(0)
	v_mfma_f32_16x16x32_bf16 v[124:127], v[144:147], v[196:199], v[124:127]
	v_mfma_f32_16x16x32_bf16 v[120:123], v[172:175], v[196:199], v[120:123]
	v_mfma_f32_16x16x32_bf16 v[116:119], v[144:147], v[204:207], v[116:119]
	v_mfma_f32_16x16x32_bf16 v[108:111], v[172:175], v[204:207], v[108:111]
	v_mfma_f32_16x16x32_bf16 v[100:103], v[144:147], v[212:215], v[100:103]
	v_mfma_f32_16x16x32_bf16 v[92:95], v[172:175], v[212:215], v[92:95]
	v_mfma_f32_16x16x32_bf16 v[84:87], v[144:147], v[220:223], v[84:87]
	v_mfma_f32_16x16x32_bf16 v[76:79], v[172:175], v[220:223], v[76:79]
	v_mfma_f32_16x16x32_bf16 v[124:127], v[164:167], v[200:203], v[124:127]
	v_mfma_f32_16x16x32_bf16 v[120:123], v[176:179], v[200:203], v[120:123]
	v_mfma_f32_16x16x32_bf16 v[116:119], v[164:167], v[208:211], v[116:119]
	v_mfma_f32_16x16x32_bf16 v[108:111], v[176:179], v[208:211], v[108:111]
	v_mfma_f32_16x16x32_bf16 v[100:103], v[164:167], v[216:219], v[100:103]
	v_mfma_f32_16x16x32_bf16 v[92:95], v[176:179], v[216:219], v[92:95]
	v_mfma_f32_16x16x32_bf16 v[84:87], v[164:167], v[224:227], v[84:87]
	v_mfma_f32_16x16x32_bf16 v[76:79], v[176:179], v[224:227], v[76:79]
	s_setprio 0
	s_setprio 1
	v_mfma_f32_16x16x32_bf16 v[112:115], v[180:183], v[196:199], v[112:115]
	v_mfma_f32_16x16x32_bf16 v[104:107], v[188:191], v[196:199], v[104:107]
	v_mfma_f32_16x16x32_bf16 v[96:99], v[180:183], v[204:207], v[96:99]
	v_mfma_f32_16x16x32_bf16 v[88:91], v[188:191], v[204:207], v[88:91]
	v_mfma_f32_16x16x32_bf16 v[80:83], v[180:183], v[212:215], v[80:83]
	v_mfma_f32_16x16x32_bf16 v[72:75], v[188:191], v[212:215], v[72:75]
	v_mfma_f32_16x16x32_bf16 v[68:71], v[180:183], v[220:223], v[68:71]
	v_mfma_f32_16x16x32_bf16 v[64:67], v[188:191], v[220:223], v[64:67]
	v_mfma_f32_16x16x32_bf16 v[112:115], v[184:187], v[200:203], v[112:115]
	v_mfma_f32_16x16x32_bf16 v[104:107], v[192:195], v[200:203], v[104:107]
	v_mfma_f32_16x16x32_bf16 v[96:99], v[184:187], v[208:211], v[96:99]
	v_mfma_f32_16x16x32_bf16 v[88:91], v[192:195], v[208:211], v[88:91]
	v_mfma_f32_16x16x32_bf16 v[80:83], v[184:187], v[216:219], v[80:83]
	v_mfma_f32_16x16x32_bf16 v[72:75], v[192:195], v[216:219], v[72:75]
	v_mfma_f32_16x16x32_bf16 v[68:71], v[184:187], v[224:227], v[68:71]
	v_mfma_f32_16x16x32_bf16 v[64:67], v[192:195], v[224:227], v[64:67]
	s_setprio 0
	s_barrier
	s_add_i32 s36, s76, s3
	s_mov_b32 m0, s36
	ds_read_b128 v[196:199], v162 offset:16384
	ds_read_b128 v[200:203], v162 offset:17408
	ds_read_b128 v[204:207], v162 offset:18432
	ds_read_b128 v[208:211], v162 offset:19456
	ds_read_b128 v[212:215], v162 offset:20480
	ds_read_b128 v[216:219], v162 offset:21504
	ds_read_b128 v[220:223], v162 offset:22528
	ds_read_b128 v[224:227], v162 offset:23552
	global_load_lds_dwordx4 v132, s[34:35]
	s_add_i32 m0, s36, 0x2000
	s_add_u32 s36, s34, 0x80000
	s_addc_u32 s37, s35, 0
	s_add_i32 s58, s77, s3
	global_load_lds_dwordx4 v128, s[34:35]
	s_mov_b32 m0, s58
	global_load_lds_dwordx4 v132, s[36:37]
	s_add_i32 m0, s58, 0x2000
	s_nop 0
	global_load_lds_dwordx4 v128, s[36:37]
	s_mov_b32 m0, s29
	s_nop 0
	global_load_lds_dwordx4 v134, s[48:49]
	s_mov_b32 m0, s53
	s_nop 0
	global_load_lds_dwordx4 v130, s[48:49]
	s_waitcnt vmcnt(8)
	s_waitcnt lgkmcnt(0)
	s_barrier
	s_setprio 1
	s_waitcnt lgkmcnt(0)
	v_mfma_f32_16x16x32_bf16 v[60:63], v[144:147], v[196:199], v[60:63]
	v_mfma_f32_16x16x32_bf16 v[56:59], v[172:175], v[196:199], v[56:59]
	v_mfma_f32_16x16x32_bf16 v[52:55], v[144:147], v[204:207], v[52:55]
	v_mfma_f32_16x16x32_bf16 v[44:47], v[172:175], v[204:207], v[44:47]
	v_mfma_f32_16x16x32_bf16 v[36:39], v[144:147], v[212:215], v[36:39]
	v_mfma_f32_16x16x32_bf16 v[28:31], v[172:175], v[212:215], v[28:31]
	v_mfma_f32_16x16x32_bf16 v[20:23], v[144:147], v[220:223], v[20:23]
	v_mfma_f32_16x16x32_bf16 v[12:15], v[172:175], v[220:223], v[12:15]
	v_mfma_f32_16x16x32_bf16 v[60:63], v[164:167], v[200:203], v[60:63]
	v_mfma_f32_16x16x32_bf16 v[56:59], v[176:179], v[200:203], v[56:59]
	v_mfma_f32_16x16x32_bf16 v[52:55], v[164:167], v[208:211], v[52:55]
	v_mfma_f32_16x16x32_bf16 v[44:47], v[176:179], v[208:211], v[44:47]
	v_mfma_f32_16x16x32_bf16 v[36:39], v[164:167], v[216:219], v[36:39]
	v_mfma_f32_16x16x32_bf16 v[28:31], v[176:179], v[216:219], v[28:31]
	v_mfma_f32_16x16x32_bf16 v[20:23], v[164:167], v[224:227], v[20:23]
	v_mfma_f32_16x16x32_bf16 v[12:15], v[176:179], v[224:227], v[12:15]
	s_setprio 0
	s_setprio 1
	v_mfma_f32_16x16x32_bf16 v[48:51], v[180:183], v[196:199], v[48:51]
	v_mfma_f32_16x16x32_bf16 v[40:43], v[188:191], v[196:199], v[40:43]
	v_mfma_f32_16x16x32_bf16 v[32:35], v[180:183], v[204:207], v[32:35]
	v_mfma_f32_16x16x32_bf16 v[24:27], v[188:191], v[204:207], v[24:27]
	v_mfma_f32_16x16x32_bf16 v[16:19], v[180:183], v[212:215], v[16:19]
	v_mfma_f32_16x16x32_bf16 v[8:11], v[188:191], v[212:215], v[8:11]
	v_mfma_f32_16x16x32_bf16 v[4:7], v[180:183], v[220:223], v[4:7]
	v_mfma_f32_16x16x32_bf16 v[0:3], v[188:191], v[220:223], v[0:3]
	v_mfma_f32_16x16x32_bf16 v[48:51], v[184:187], v[200:203], v[48:51]
	v_mfma_f32_16x16x32_bf16 v[40:43], v[192:195], v[200:203], v[40:43]
	v_mfma_f32_16x16x32_bf16 v[32:35], v[184:187], v[208:211], v[32:35]
	v_mfma_f32_16x16x32_bf16 v[24:27], v[192:195], v[208:211], v[24:27]
	v_mfma_f32_16x16x32_bf16 v[16:19], v[184:187], v[216:219], v[16:19]
	v_mfma_f32_16x16x32_bf16 v[8:11], v[192:195], v[216:219], v[8:11]
	v_mfma_f32_16x16x32_bf16 v[4:7], v[184:187], v[224:227], v[4:7]
	v_mfma_f32_16x16x32_bf16 v[0:3], v[192:195], v[224:227], v[0:3]
	s_setprio 0
	s_barrier
; #define PG8_STAGE(bufoff, gbase, voff) do { _Pragma("unroll") for (int _i = 0; _i < 2; ++_i) \
;         __builtin_amdgcn_global_load_lds((const unsigned*)((const char*)(gbase) + (voff)[_i]), (PG8_LAS unsigned*)(lds + (bufoff) + ldsw + _i * 8192), 16, 0, 0); } while (0)
; #define PG8_LDA(dst, b, h) do { _Pragma("unroll") for (int m = 0; m < 4; ++m) _Pragma("unroll") for (int k = 0; k < 2; ++k) dst[m][k] = *(const PG8_LAS bf16x8*)(lds + PG8_SA(b, h) + aoff + m * 2048 + k * 1024); } while (0)
; #define PG8_LDB(dst, b, h) do { _Pragma("unroll") for (int n = 0; n < 2; ++n) _Pragma("unroll") for (int k = 0; k < 2; ++k) dst[n][k] = *(const PG8_LAS bf16x8*)(lds + PG8_SB(b, h) + boff + n * 2048 + k * 1024); } while (0)
; template <class Epi, class Sched, bool ALIGN_EPI = false, bool SP2 = false>
; __device__ __forceinline__ void gemm_phase(PG8_LAS unsigned char* lds, const Gemm g, const Sched& S, const Epi& E) {
;     ...
;         for (int t = 0; t < nt; t += 2) {
;             const bool last = (t == nt - 2);
;             const char* a1 = cA + (size_t)(t + 1) * kstep;
;             const char* a2 = last ? nA : cA + (size_t)(t + 2) * kstep; const char* b2 = last ? nB : cB + (size_t)(t + 2) * kstep;
;             const char* a3 = a2 + kstep; const char* b3 = b2 + kstep;
;             if (last && has_next) S.a_ready(nxt);
;             if constexpr (SP2) {
;             PG8_LDB(B0, 0, 0); PG8_LDB(B1, 0, 1); PG8_SCHED; PG8_LDA(At, 0, 0); PG8_STAGE(PG8_SA(1, 1), a1 + hstep, voffA);
;             PG8_WAIT_V(8); PG8_WAIT_L(0); PG8_BAR; PG8_MMA(0, 0, At, B0); PG8_MMA(0, 1, At, B1); PG8_BAR; PG8_SCHED;
;             PG8_LDA(At, 0, 1); PG8_STAGE(PG8_SB(0, 0), b2, voffB); PG8_STAGE(PG8_SB(0, 1), b2 + hstep, voffB); PG8_STAGE(PG8_SA(0, 0), a2, voffA);
;             PG8_WAIT_V(8); PG8_WAIT_L(0); PG8_BAR; PG8_MMA(1, 0, At, B0); PG8_MMA(1, 1, At, B1); PG8_BAR; PG8_SCHED;
;             PG8_LDB(B0, 1, 0); PG8_LDB(B1, 1, 1); PG8_SCHED; PG8_LDA(At, 1, 0); PG8_STAGE(PG8_SA(0, 1), a2 + hstep, voffA);
;             PG8_WAIT_V(8); PG8_WAIT_L(0); PG8_BAR; PG8_MMA(0, 0, At, B0); PG8_MMA(0, 1, At, B1); PG8_BAR; PG8_SCHED;
;             PG8_LDA(At, 1, 1); PG8_STAGE(PG8_SB(1, 0), b3, voffB); PG8_STAGE(PG8_SB(1, 1), b3 + hstep, voffB); PG8_STAGE(PG8_SA(1, 0), a3, voffA);
;             PG8_WAIT_V(8); PG8_WAIT_L(0); PG8_BAR; PG8_MMA(1, 0, At, B0); PG8_MMA(1, 1, At, B1); PG8_BAR; PG8_SCHED;
	s_add_i32 s58, 0, 0x18000
	v_add_u32_e32 v163, s58, v158
	s_add_i32 s59, 0, 0x1c000
	ds_read_b128 v[144:147], v163
	ds_read_b128 v[164:167], v163 offset:1024
	ds_read_b128 v[172:175], v163 offset:2048
	ds_read_b128 v[176:179], v163 offset:3072
	v_add_u32_e32 v163, s59, v158
	ds_read_b128 v[180:183], v163
	ds_read_b128 v[184:187], v163 offset:1024
	ds_read_b128 v[188:191], v163 offset:2048
	ds_read_b128 v[192:195], v163 offset:3072
	s_add_u32 s36, s48, 0x80000
	s_addc_u32 s37, s49, 0
	s_mov_b32 m0, s54
	ds_read_b128 v[196:199], v162 offset:32768
	ds_read_b128 v[200:203], v162 offset:33792
	ds_read_b128 v[204:207], v162 offset:34816
	ds_read_b128 v[208:211], v162 offset:35840
	ds_read_b128 v[212:215], v162 offset:36864
	ds_read_b128 v[216:219], v162 offset:37888
	ds_read_b128 v[220:223], v162 offset:38912
	ds_read_b128 v[224:227], v162 offset:39936
	global_load_lds_dwordx4 v134, s[36:37]
	s_mov_b32 m0, s55
	s_nop 0
	global_load_lds_dwordx4 v130, s[36:37]
	s_waitcnt vmcnt(8)
	s_waitcnt lgkmcnt(0)
	s_barrier
	s_setprio 1
	s_waitcnt lgkmcnt(0)
	v_mfma_f32_16x16x32_bf16 v[124:127], v[144:147], v[196:199], v[124:127]
	v_mfma_f32_16x16x32_bf16 v[120:123], v[172:175], v[196:199], v[120:123]
	v_mfma_f32_16x16x32_bf16 v[116:119], v[144:147], v[204:207], v[116:119]
	v_mfma_f32_16x16x32_bf16 v[108:111], v[172:175], v[204:207], v[108:111]
	v_mfma_f32_16x16x32_bf16 v[100:103], v[144:147], v[212:215], v[100:103]
	v_mfma_f32_16x16x32_bf16 v[92:95], v[172:175], v[212:215], v[92:95]
	v_mfma_f32_16x16x32_bf16 v[84:87], v[144:147], v[220:223], v[84:87]
	v_mfma_f32_16x16x32_bf16 v[76:79], v[172:175], v[220:223], v[76:79]
	v_mfma_f32_16x16x32_bf16 v[124:127], v[164:167], v[200:203], v[124:127]
	v_mfma_f32_16x16x32_bf16 v[120:123], v[176:179], v[200:203], v[120:123]
	v_mfma_f32_16x16x32_bf16 v[116:119], v[164:167], v[208:211], v[116:119]
	v_mfma_f32_16x16x32_bf16 v[108:111], v[176:179], v[208:211], v[108:111]
	v_mfma_f32_16x16x32_bf16 v[100:103], v[164:167], v[216:219], v[100:103]
	v_mfma_f32_16x16x32_bf16 v[92:95], v[176:179], v[216:219], v[92:95]
	v_mfma_f32_16x16x32_bf16 v[84:87], v[164:167], v[224:227], v[84:87]
	v_mfma_f32_16x16x32_bf16 v[76:79], v[176:179], v[224:227], v[76:79]
	s_setprio 0
	s_setprio 1
	v_mfma_f32_16x16x32_bf16 v[112:115], v[180:183], v[196:199], v[112:115]
	v_mfma_f32_16x16x32_bf16 v[104:107], v[188:191], v[196:199], v[104:107]
	v_mfma_f32_16x16x32_bf16 v[96:99], v[180:183], v[204:207], v[96:99]
	v_mfma_f32_16x16x32_bf16 v[88:91], v[188:191], v[204:207], v[88:91]
	v_mfma_f32_16x16x32_bf16 v[80:83], v[180:183], v[212:215], v[80:83]
	v_mfma_f32_16x16x32_bf16 v[72:75], v[188:191], v[212:215], v[72:75]
	v_mfma_f32_16x16x32_bf16 v[68:71], v[180:183], v[220:223], v[68:71]
	v_mfma_f32_16x16x32_bf16 v[64:67], v[188:191], v[220:223], v[64:67]
	v_mfma_f32_16x16x32_bf16 v[112:115], v[184:187], v[200:203], v[112:115]
	v_mfma_f32_16x16x32_bf16 v[104:107], v[192:195], v[200:203], v[104:107]
	v_mfma_f32_16x16x32_bf16 v[96:99], v[184:187], v[208:211], v[96:99]
	v_mfma_f32_16x16x32_bf16 v[88:91], v[192:195], v[208:211], v[88:91]
	v_mfma_f32_16x16x32_bf16 v[80:83], v[184:187], v[216:219], v[80:83]
	v_mfma_f32_16x16x32_bf16 v[72:75], v[192:195], v[216:219], v[72:75]
	v_mfma_f32_16x16x32_bf16 v[68:71], v[184:187], v[224:227], v[68:71]
	v_mfma_f32_16x16x32_bf16 v[64:67], v[192:195], v[224:227], v[64:67]
	s_setprio 0
	s_barrier
	s_add_i32 s36, s58, s3
	s_add_i32 m0, s36, 0xffffff80
	ds_read_b128 v[196:199], v162 offset:49152
	ds_read_b128 v[200:203], v162 offset:50176
	ds_read_b128 v[204:207], v162 offset:51200
	ds_read_b128 v[208:211], v162 offset:52224
	ds_read_b128 v[212:215], v162 offset:53248
	ds_read_b128 v[216:219], v162 offset:54272
	ds_read_b128 v[220:223], v162 offset:55296
	ds_read_b128 v[224:227], v162 offset:56320
	global_load_lds_dwordx4 v132, s[34:35] offset:128
	s_add_i32 m0, s36, 0x1f80
	s_nop 0
	global_load_lds_dwordx4 v128, s[34:35] offset:128
	s_add_u32 s34, s34, 0x80080
	s_addc_u32 s35, s35, 0
	s_add_i32 s36, s59, s3
	s_mov_b32 m0, s36
	s_nop 0
	global_load_lds_dwordx4 v132, s[34:35]
	s_add_i32 m0, s36, 0x2000
	s_nop 0
	global_load_lds_dwordx4 v128, s[34:35]
	s_add_i32 m0, s68, 0xffffff80
	s_nop 0
	global_load_lds_dwordx4 v134, s[48:49] offset:128
	s_add_i32 m0, s69, 0xffffff80
	s_nop 0
	global_load_lds_dwordx4 v130, s[48:49] offset:128
	s_waitcnt vmcnt(8)
	s_waitcnt lgkmcnt(0)
	s_barrier
	s_setprio 1
	s_waitcnt lgkmcnt(0)
	v_mfma_f32_16x16x32_bf16 v[60:63], v[144:147], v[196:199], v[60:63]
	v_mfma_f32_16x16x32_bf16 v[56:59], v[172:175], v[196:199], v[56:59]
	v_mfma_f32_16x16x32_bf16 v[52:55], v[144:147], v[204:207], v[52:55]
	v_mfma_f32_16x16x32_bf16 v[44:47], v[172:175], v[204:207], v[44:47]
	v_mfma_f32_16x16x32_bf16 v[36:39], v[144:147], v[212:215], v[36:39]
	v_mfma_f32_16x16x32_bf16 v[28:31], v[172:175], v[212:215], v[28:31]
	v_mfma_f32_16x16x32_bf16 v[20:23], v[144:147], v[220:223], v[20:23]
	v_mfma_f32_16x16x32_bf16 v[12:15], v[172:175], v[220:223], v[12:15]
	v_mfma_f32_16x16x32_bf16 v[60:63], v[164:167], v[200:203], v[60:63]
	v_mfma_f32_16x16x32_bf16 v[56:59], v[176:179], v[200:203], v[56:59]
	v_mfma_f32_16x16x32_bf16 v[52:55], v[164:167], v[208:211], v[52:55]
	v_mfma_f32_16x16x32_bf16 v[44:47], v[176:179], v[208:211], v[44:47]
	v_mfma_f32_16x16x32_bf16 v[36:39], v[164:167], v[216:219], v[36:39]
	v_mfma_f32_16x16x32_bf16 v[28:31], v[176:179], v[216:219], v[28:31]
	v_mfma_f32_16x16x32_bf16 v[20:23], v[164:167], v[224:227], v[20:23]
	v_mfma_f32_16x16x32_bf16 v[12:15], v[176:179], v[224:227], v[12:15]
	s_setprio 0
	s_setprio 1
	v_mfma_f32_16x16x32_bf16 v[48:51], v[180:183], v[196:199], v[48:51]
	v_mfma_f32_16x16x32_bf16 v[40:43], v[188:191], v[196:199], v[40:43]
	v_mfma_f32_16x16x32_bf16 v[32:35], v[180:183], v[204:207], v[32:35]
	v_mfma_f32_16x16x32_bf16 v[24:27], v[188:191], v[204:207], v[24:27]
	v_mfma_f32_16x16x32_bf16 v[16:19], v[180:183], v[212:215], v[16:19]
	v_mfma_f32_16x16x32_bf16 v[8:11], v[188:191], v[212:215], v[8:11]
	v_mfma_f32_16x16x32_bf16 v[4:7], v[180:183], v[220:223], v[4:7]
	v_mfma_f32_16x16x32_bf16 v[0:3], v[188:191], v[220:223], v[0:3]
	v_mfma_f32_16x16x32_bf16 v[48:51], v[184:187], v[200:203], v[48:51]
	v_mfma_f32_16x16x32_bf16 v[40:43], v[192:195], v[200:203], v[40:43]
	v_mfma_f32_16x16x32_bf16 v[32:35], v[184:187], v[208:211], v[32:35]
	v_mfma_f32_16x16x32_bf16 v[24:27], v[192:195], v[208:211], v[24:27]
	v_mfma_f32_16x16x32_bf16 v[16:19], v[184:187], v[216:219], v[16:19]
	v_mfma_f32_16x16x32_bf16 v[8:11], v[192:195], v[216:219], v[8:11]
	v_mfma_f32_16x16x32_bf16 v[4:7], v[184:187], v[224:227], v[4:7]
	v_mfma_f32_16x16x32_bf16 v[0:3], v[192:195], v[224:227], v[0:3]
	s_setprio 0
	s_barrier
	s_add_i32 s84, s84, 2
	s_add_u32 s30, s30, 0x100
	s_addc_u32 s31, s31, 0
	s_add_u32 s82, s82, 0x100
	s_addc_u32 s83, s83, 0
	s_cmp_gt_u32 s84, 29
	s_cbranch_scc0 .LBB0_139
	s_and_b64 vcc, exec, s[14:15]
	s_cbranch_vccz .LBB0_142
	s_barrier

; #define PG8_STAGE(bufoff, gbase, voff) do { _Pragma("unroll") for (int _i = 0; _i < 2; ++_i) \
;         __builtin_amdgcn_global_load_lds((const unsigned*)((const char*)(gbase) + (voff)[_i]), (PG8_LAS unsigned*)(lds + (bufoff) + ldsw + _i * 8192), 16, 0, 0); } while (0)
; #define PG8_LDA(dst, b, h) do { _Pragma("unroll") for (int m = 0; m < 4; ++m) _Pragma("unroll") for (int k = 0; k < 2; ++k) dst[m][k] = *(const PG8_LAS bf16x8*)(lds + PG8_SA(b, h) + aoff + m * 2048 + k * 1024); } while (0)
; #define PG8_LDB(dst, b, h) do { _Pragma("unroll") for (int n = 0; n < 2; ++n) _Pragma("unroll") for (int k = 0; k < 2; ++k) dst[n][k] = *(const PG8_LAS bf16x8*)(lds + PG8_SB(b, h) + boff + n * 2048 + k * 1024); } while (0)
; #define PG8_MMA(ai, bj, At, Bt) do { __builtin_amdgcn_s_setprio(1); _Pragma("unroll") for (int m = 0; m < 4; ++m) _Pragma("unroll") for (int n = 0; n < 2; ++n) _Pragma("unroll") for (int k = 0; k < 2; ++k) \
;         acc[ai][bj][m][n] = __builtin_amdgcn_mfma_f32_16x16x32_bf16(Bt[n][k], At[m][k], acc[ai][bj][m][n], 0, 0, 0); __builtin_amdgcn_s_setprio(0); } while (0)
; #define PG8_WAIT_V(n) asm volatile("s_waitcnt vmcnt(" #n ")" ::: "memory")
; #define PG8_WAIT_L(n) asm volatile("s_waitcnt lgkmcnt(" #n ")" ::: "memory")
; #define PG8_BAR __builtin_amdgcn_s_barrier()
; #define PG8_SCHED __builtin_amdgcn_sched_barrier(0)
; template <class Epi, class Sched, bool ALIGN_EPI = false, bool SP2 = false>
; __device__ __forceinline__ void gemm_phase(PG8_LAS unsigned char* lds, const Gemm g, const Sched& S, const Epi& E) {
;     ...
;             PG8_LDB(B0, 0, 0); PG8_LDB(B1, 0, 1); PG8_SCHED; PG8_LDA(At, 0, 0); PG8_STAGE(PG8_SA(1, 1), a1 + hstep, voffA);
;             PG8_WAIT_V(8); PG8_WAIT_L(0); PG8_BAR; PG8_MMA(0, 0, At, B0); PG8_MMA(0, 1, At, B1); PG8_BAR; PG8_SCHED;
;             PG8_LDA(At, 0, 1); PG8_STAGE(PG8_SB(0, 0), b2, voffB); PG8_STAGE(PG8_SB(0, 1), b2 + hstep, voffB); PG8_STAGE(PG8_SA(0, 0), a2, voffA);
;             PG8_WAIT_V(8); PG8_WAIT_L(0); PG8_BAR; PG8_MMA(1, 0, At, B0); PG8_MMA(1, 1, At, B1); PG8_BAR; PG8_SCHED;
.LBB0_393:
	ds_read_b128 v[146:149], v156
	ds_read_b128 v[150:153], v156 offset:1024
	ds_read_b128 v[160:163], v156 offset:2048
	ds_read_b128 v[164:167], v156 offset:3072
	ds_read_b128 v[172:175], v157
	ds_read_b128 v[176:179], v157 offset:1024
	ds_read_b128 v[180:183], v157 offset:2048
	ds_read_b128 v[184:187], v157 offset:3072
	s_add_u32 s34, s30, 0xfff80080
	s_addc_u32 s35, s31, -1
	s_cmp_eq_u32 s81, 28
	s_cselect_b32 s49, s23, s35
	s_cselect_b32 s48, s77, s34
	s_cselect_b32 s35, s21, s80
	s_cselect_b32 s34, s78, s79
	s_add_i32 m0, s29, 0xc000
	ds_read_b128 v[188:191], v158
	ds_read_b128 v[192:195], v158 offset:1024
	ds_read_b128 v[196:199], v158 offset:2048
	ds_read_b128 v[200:203], v158 offset:3072
	ds_read_b128 v[204:207], v158 offset:4096
	ds_read_b128 v[208:211], v158 offset:5120
	ds_read_b128 v[212:215], v158 offset:6144
	ds_read_b128 v[216:219], v158 offset:7168
	global_load_lds_dwordx4 v138, s[30:31]
	s_add_i32 m0, s29, 0xe000
	s_nop 0
	global_load_lds_dwordx4 v140, s[30:31]
	s_waitcnt vmcnt(8)
	s_waitcnt lgkmcnt(0)
	s_barrier
	s_setprio 1
	s_waitcnt lgkmcnt(0)
	v_mfma_f32_16x16x32_bf16 v[124:127], v[146:149], v[188:191], v[124:127]
	v_mfma_f32_16x16x32_bf16 v[120:123], v[160:163], v[188:191], v[120:123]
	v_mfma_f32_16x16x32_bf16 v[116:119], v[146:149], v[196:199], v[116:119]
	v_mfma_f32_16x16x32_bf16 v[112:115], v[160:163], v[196:199], v[112:115]
	v_mfma_f32_16x16x32_bf16 v[108:111], v[146:149], v[204:207], v[108:111]
	v_mfma_f32_16x16x32_bf16 v[104:107], v[160:163], v[204:207], v[104:107]
	v_mfma_f32_16x16x32_bf16 v[100:103], v[146:149], v[212:215], v[100:103]
	v_mfma_f32_16x16x32_bf16 v[96:99], v[160:163], v[212:215], v[96:99]
	v_mfma_f32_16x16x32_bf16 v[124:127], v[150:153], v[192:195], v[124:127]
	v_mfma_f32_16x16x32_bf16 v[120:123], v[164:167], v[192:195], v[120:123]
	v_mfma_f32_16x16x32_bf16 v[116:119], v[150:153], v[200:203], v[116:119]
	v_mfma_f32_16x16x32_bf16 v[112:115], v[164:167], v[200:203], v[112:115]
	v_mfma_f32_16x16x32_bf16 v[108:111], v[150:153], v[208:211], v[108:111]
	v_mfma_f32_16x16x32_bf16 v[104:107], v[164:167], v[208:211], v[104:107]
	v_mfma_f32_16x16x32_bf16 v[100:103], v[150:153], v[216:219], v[100:103]
	v_mfma_f32_16x16x32_bf16 v[96:99], v[164:167], v[216:219], v[96:99]
	s_setprio 0
	s_setprio 1
	v_mfma_f32_16x16x32_bf16 v[60:63], v[172:175], v[188:191], v[60:63]
	v_mfma_f32_16x16x32_bf16 v[56:59], v[180:183], v[188:191], v[56:59]
	v_mfma_f32_16x16x32_bf16 v[52:55], v[172:175], v[196:199], v[52:55]
	v_mfma_f32_16x16x32_bf16 v[48:51], v[180:183], v[196:199], v[48:51]
	v_mfma_f32_16x16x32_bf16 v[44:47], v[172:175], v[204:207], v[44:47]
	v_mfma_f32_16x16x32_bf16 v[40:43], v[180:183], v[204:207], v[40:43]
	v_mfma_f32_16x16x32_bf16 v[36:39], v[172:175], v[212:215], v[36:39]
	v_mfma_f32_16x16x32_bf16 v[32:35], v[180:183], v[212:215], v[32:35]
	v_mfma_f32_16x16x32_bf16 v[60:63], v[176:179], v[192:195], v[60:63]
	v_mfma_f32_16x16x32_bf16 v[56:59], v[184:187], v[192:195], v[56:59]
	v_mfma_f32_16x16x32_bf16 v[52:55], v[176:179], v[200:203], v[52:55]
	v_mfma_f32_16x16x32_bf16 v[48:51], v[184:187], v[200:203], v[48:51]
	v_mfma_f32_16x16x32_bf16 v[44:47], v[176:179], v[208:211], v[44:47]
	v_mfma_f32_16x16x32_bf16 v[40:43], v[184:187], v[208:211], v[40:43]
	v_mfma_f32_16x16x32_bf16 v[36:39], v[176:179], v[216:219], v[36:39]
	v_mfma_f32_16x16x32_bf16 v[32:35], v[184:187], v[216:219], v[32:35]
	s_setprio 0
	s_barrier
	s_add_i32 s36, s74, s19
	s_mov_b32 m0, s36
	ds_read_b128 v[188:191], v158 offset:16384
	ds_read_b128 v[192:195], v158 offset:17408
	ds_read_b128 v[196:199], v158 offset:18432
	ds_read_b128 v[200:203], v158 offset:19456
	ds_read_b128 v[204:207], v158 offset:20480
	ds_read_b128 v[208:211], v158 offset:21504
	ds_read_b128 v[212:215], v158 offset:22528
	ds_read_b128 v[216:219], v158 offset:23552
	global_load_lds_dwordx4 v130, s[34:35]
	s_add_i32 m0, s36, 0x2000
	s_add_u32 s36, s34, 0x80000
	s_addc_u32 s37, s35, 0
	s_add_i32 s58, s75, s19
	global_load_lds_dwordx4 v134, s[34:35]
	s_mov_b32 m0, s58
	global_load_lds_dwordx4 v130, s[36:37]
	s_add_i32 m0, s58, 0x2000
	s_nop 0
	global_load_lds_dwordx4 v134, s[36:37]
	s_mov_b32 m0, s29
	s_nop 0
	global_load_lds_dwordx4 v128, s[48:49]
	s_mov_b32 m0, s39
	s_nop 0
	global_load_lds_dwordx4 v132, s[48:49]
	s_waitcnt vmcnt(8)
	s_waitcnt lgkmcnt(0)
	s_barrier
	s_setprio 1
	s_waitcnt lgkmcnt(0)
	v_mfma_f32_16x16x32_bf16 v[92:95], v[146:149], v[188:191], v[92:95]
	v_mfma_f32_16x16x32_bf16 v[88:91], v[160:163], v[188:191], v[88:91]
	v_mfma_f32_16x16x32_bf16 v[84:87], v[146:149], v[196:199], v[84:87]
	v_mfma_f32_16x16x32_bf16 v[80:83], v[160:163], v[196:199], v[80:83]
	v_mfma_f32_16x16x32_bf16 v[76:79], v[146:149], v[204:207], v[76:79]
	v_mfma_f32_16x16x32_bf16 v[72:75], v[160:163], v[204:207], v[72:75]
	v_mfma_f32_16x16x32_bf16 v[68:71], v[146:149], v[212:215], v[68:71]
	v_mfma_f32_16x16x32_bf16 v[64:67], v[160:163], v[212:215], v[64:67]
	v_mfma_f32_16x16x32_bf16 v[92:95], v[150:153], v[192:195], v[92:95]
	v_mfma_f32_16x16x32_bf16 v[88:91], v[164:167], v[192:195], v[88:91]
	v_mfma_f32_16x16x32_bf16 v[84:87], v[150:153], v[200:203], v[84:87]
	v_mfma_f32_16x16x32_bf16 v[80:83], v[164:167], v[200:203], v[80:83]
	v_mfma_f32_16x16x32_bf16 v[76:79], v[150:153], v[208:211], v[76:79]
	v_mfma_f32_16x16x32_bf16 v[72:75], v[164:167], v[208:211], v[72:75]
	v_mfma_f32_16x16x32_bf16 v[68:71], v[150:153], v[216:219], v[68:71]
	v_mfma_f32_16x16x32_bf16 v[64:67], v[164:167], v[216:219], v[64:67]
	s_setprio 0
	s_setprio 1
	v_mfma_f32_16x16x32_bf16 v[28:31], v[172:175], v[188:191], v[28:31]
	v_mfma_f32_16x16x32_bf16 v[24:27], v[180:183], v[188:191], v[24:27]
	v_mfma_f32_16x16x32_bf16 v[20:23], v[172:175], v[196:199], v[20:23]
	v_mfma_f32_16x16x32_bf16 v[16:19], v[180:183], v[196:199], v[16:19]
	v_mfma_f32_16x16x32_bf16 v[12:15], v[172:175], v[204:207], v[12:15]
	v_mfma_f32_16x16x32_bf16 v[8:11], v[180:183], v[204:207], v[8:11]
	v_mfma_f32_16x16x32_bf16 v[4:7], v[172:175], v[212:215], v[4:7]
	v_mfma_f32_16x16x32_bf16 v[0:3], v[180:183], v[212:215], v[0:3]
	v_mfma_f32_16x16x32_bf16 v[28:31], v[176:179], v[192:195], v[28:31]
	v_mfma_f32_16x16x32_bf16 v[24:27], v[184:187], v[192:195], v[24:27]
	v_mfma_f32_16x16x32_bf16 v[20:23], v[176:179], v[200:203], v[20:23]
	v_mfma_f32_16x16x32_bf16 v[16:19], v[184:187], v[200:203], v[16:19]
	v_mfma_f32_16x16x32_bf16 v[12:15], v[176:179], v[208:211], v[12:15]
	v_mfma_f32_16x16x32_bf16 v[8:11], v[184:187], v[208:211], v[8:11]
	v_mfma_f32_16x16x32_bf16 v[4:7], v[176:179], v[216:219], v[4:7]
	v_mfma_f32_16x16x32_bf16 v[0:3], v[184:187], v[216:219], v[0:3]
	s_setprio 0
	s_barrier
; #define PG8_STAGE(bufoff, gbase, voff) do { _Pragma("unroll") for (int _i = 0; _i < 2; ++_i) \
;         __builtin_amdgcn_global_load_lds((const unsigned*)((const char*)(gbase) + (voff)[_i]), (PG8_LAS unsigned*)(lds + (bufoff) + ldsw + _i * 8192), 16, 0, 0); } while (0)
; #define PG8_LDA(dst, b, h) do { _Pragma("unroll") for (int m = 0; m < 4; ++m) _Pragma("unroll") for (int k = 0; k < 2; ++k) dst[m][k] = *(const PG8_LAS bf16x8*)(lds + PG8_SA(b, h) + aoff + m * 2048 + k * 1024); } while (0)
; #define PG8_LDB(dst, b, h) do { _Pragma("unroll") for (int n = 0; n < 2; ++n) _Pragma("unroll") for (int k = 0; k < 2; ++k) dst[n][k] = *(const PG8_LAS bf16x8*)(lds + PG8_SB(b, h) + boff + n * 2048 + k * 1024); } while (0)
; template <class Epi, class Sched, bool ALIGN_EPI = false, bool SP2 = false>
; __device__ __forceinline__ void gemm_phase(PG8_LAS unsigned char* lds, const Gemm g, const Sched& S, const Epi& E) {
;     ...
;         for (int t = 0; t < nt; t += 2) {
;             const bool last = (t == nt - 2);
;             const char* a1 = cA + (size_t)(t + 1) * kstep;
;             const char* a2 = last ? nA : cA + (size_t)(t + 2) * kstep; const char* b2 = last ? nB : cB + (size_t)(t + 2) * kstep;
;             const char* a3 = a2 + kstep; const char* b3 = b2 + kstep;
;             if (last && has_next) S.a_ready(nxt);
;             if constexpr (SP2) {
;             PG8_LDB(B0, 0, 0); PG8_LDB(B1, 0, 1); PG8_SCHED; PG8_LDA(At, 0, 0); PG8_STAGE(PG8_SA(1, 1), a1 + hstep, voffA);
;             PG8_WAIT_V(8); PG8_WAIT_L(0); PG8_BAR; PG8_MMA(0, 0, At, B0); PG8_MMA(0, 1, At, B1); PG8_BAR; PG8_SCHED;
;             PG8_LDA(At, 0, 1); PG8_STAGE(PG8_SB(0, 0), b2, voffB); PG8_STAGE(PG8_SB(0, 1), b2 + hstep, voffB); PG8_STAGE(PG8_SA(0, 0), a2, voffA);
;             PG8_WAIT_V(8); PG8_WAIT_L(0); PG8_BAR; PG8_MMA(1, 0, At, B0); PG8_MMA(1, 1, At, B1); PG8_BAR; PG8_SCHED;
;             PG8_LDB(B0, 1, 0); PG8_LDB(B1, 1, 1); PG8_SCHED; PG8_LDA(At, 1, 0); PG8_STAGE(PG8_SA(0, 1), a2 + hstep, voffA);
;             PG8_WAIT_V(8); PG8_WAIT_L(0); PG8_BAR; PG8_MMA(0, 0, At, B0); PG8_MMA(0, 1, At, B1); PG8_BAR; PG8_SCHED;
;             PG8_LDA(At, 1, 1); PG8_STAGE(PG8_SB(1, 0), b3, voffB); PG8_STAGE(PG8_SB(1, 1), b3 + hstep, voffB); PG8_STAGE(PG8_SA(1, 0), a3, voffA);
;             PG8_WAIT_V(8); PG8_WAIT_L(0); PG8_BAR; PG8_MMA(1, 0, At, B0); PG8_MMA(1, 1, At, B1); PG8_BAR; PG8_SCHED;
	s_add_i32 s58, 0, 0x18000
	v_add_u32_e32 v136, s58, v154
	s_add_i32 s59, 0, 0x1c000
	ds_read_b128 v[146:149], v136
	ds_read_b128 v[150:153], v136 offset:1024
	ds_read_b128 v[160:163], v136 offset:2048
	ds_read_b128 v[164:167], v136 offset:3072
	v_add_u32_e32 v136, s59, v154
	ds_read_b128 v[172:175], v136
	ds_read_b128 v[176:179], v136 offset:1024
	ds_read_b128 v[180:183], v136 offset:2048
	ds_read_b128 v[184:187], v136 offset:3072
	s_add_u32 s36, s48, 0x80000
	s_addc_u32 s37, s49, 0
	s_mov_b32 m0, s50
	ds_read_b128 v[188:191], v158 offset:32768
	ds_read_b128 v[192:195], v158 offset:33792
	ds_read_b128 v[196:199], v158 offset:34816
	ds_read_b128 v[200:203], v158 offset:35840
	ds_read_b128 v[204:207], v158 offset:36864
	ds_read_b128 v[208:211], v158 offset:37888
	ds_read_b128 v[212:215], v158 offset:38912
	ds_read_b128 v[216:219], v158 offset:39936
	global_load_lds_dwordx4 v128, s[36:37]
	s_mov_b32 m0, s51
	s_nop 0
	global_load_lds_dwordx4 v132, s[36:37]
	s_waitcnt vmcnt(8)
	s_waitcnt lgkmcnt(0)
	s_barrier
	s_setprio 1
	s_waitcnt lgkmcnt(0)
	v_mfma_f32_16x16x32_bf16 v[124:127], v[146:149], v[188:191], v[124:127]
	v_mfma_f32_16x16x32_bf16 v[120:123], v[160:163], v[188:191], v[120:123]
	v_mfma_f32_16x16x32_bf16 v[116:119], v[146:149], v[196:199], v[116:119]
	v_mfma_f32_16x16x32_bf16 v[112:115], v[160:163], v[196:199], v[112:115]
	v_mfma_f32_16x16x32_bf16 v[108:111], v[146:149], v[204:207], v[108:111]
	v_mfma_f32_16x16x32_bf16 v[104:107], v[160:163], v[204:207], v[104:107]
	v_mfma_f32_16x16x32_bf16 v[100:103], v[146:149], v[212:215], v[100:103]
	v_mfma_f32_16x16x32_bf16 v[96:99], v[160:163], v[212:215], v[96:99]
	v_mfma_f32_16x16x32_bf16 v[124:127], v[150:153], v[192:195], v[124:127]
	v_mfma_f32_16x16x32_bf16 v[120:123], v[164:167], v[192:195], v[120:123]
	v_mfma_f32_16x16x32_bf16 v[116:119], v[150:153], v[200:203], v[116:119]
	v_mfma_f32_16x16x32_bf16 v[112:115], v[164:167], v[200:203], v[112:115]
	v_mfma_f32_16x16x32_bf16 v[108:111], v[150:153], v[208:211], v[108:111]
	v_mfma_f32_16x16x32_bf16 v[104:107], v[164:167], v[208:211], v[104:107]
	v_mfma_f32_16x16x32_bf16 v[100:103], v[150:153], v[216:219], v[100:103]
	v_mfma_f32_16x16x32_bf16 v[96:99], v[164:167], v[216:219], v[96:99]
	s_setprio 0
	s_setprio 1
	v_mfma_f32_16x16x32_bf16 v[60:63], v[172:175], v[188:191], v[60:63]
	v_mfma_f32_16x16x32_bf16 v[56:59], v[180:183], v[188:191], v[56:59]
	v_mfma_f32_16x16x32_bf16 v[52:55], v[172:175], v[196:199], v[52:55]
	v_mfma_f32_16x16x32_bf16 v[48:51], v[180:183], v[196:199], v[48:51]
	v_mfma_f32_16x16x32_bf16 v[44:47], v[172:175], v[204:207], v[44:47]
	v_mfma_f32_16x16x32_bf16 v[40:43], v[180:183], v[204:207], v[40:43]
	v_mfma_f32_16x16x32_bf16 v[36:39], v[172:175], v[212:215], v[36:39]
	v_mfma_f32_16x16x32_bf16 v[32:35], v[180:183], v[212:215], v[32:35]
	v_mfma_f32_16x16x32_bf16 v[60:63], v[176:179], v[192:195], v[60:63]
	v_mfma_f32_16x16x32_bf16 v[56:59], v[184:187], v[192:195], v[56:59]
	v_mfma_f32_16x16x32_bf16 v[52:55], v[176:179], v[200:203], v[52:55]
	v_mfma_f32_16x16x32_bf16 v[48:51], v[184:187], v[200:203], v[48:51]
	v_mfma_f32_16x16x32_bf16 v[44:47], v[176:179], v[208:211], v[44:47]
	v_mfma_f32_16x16x32_bf16 v[40:43], v[184:187], v[208:211], v[40:43]
	v_mfma_f32_16x16x32_bf16 v[36:39], v[176:179], v[216:219], v[36:39]
	v_mfma_f32_16x16x32_bf16 v[32:35], v[184:187], v[216:219], v[32:35]
	s_setprio 0
	s_barrier
	s_add_i32 s36, s58, s19
	s_add_i32 m0, s36, 0xffffff80
	ds_read_b128 v[188:191], v158 offset:49152
	ds_read_b128 v[192:195], v158 offset:50176
	ds_read_b128 v[196:199], v158 offset:51200
	ds_read_b128 v[200:203], v158 offset:52224
	ds_read_b128 v[204:207], v158 offset:53248
	ds_read_b128 v[208:211], v158 offset:54272
	ds_read_b128 v[212:215], v158 offset:55296
	ds_read_b128 v[216:219], v158 offset:56320
	global_load_lds_dwordx4 v130, s[34:35] offset:128
	s_add_i32 m0, s36, 0x1f80
	s_nop 0
	global_load_lds_dwordx4 v134, s[34:35] offset:128
	s_add_u32 s34, s34, 0x80080
	s_addc_u32 s35, s35, 0
	s_add_i32 s36, s59, s19
	s_mov_b32 m0, s36
	s_nop 0
	global_load_lds_dwordx4 v130, s[34:35]
	s_add_i32 m0, s36, 0x2000
	s_nop 0
	global_load_lds_dwordx4 v134, s[34:35]
	s_add_i32 m0, s53, 0xffffff80
	s_nop 0
	global_load_lds_dwordx4 v128, s[48:49] offset:128
	s_add_i32 m0, s54, 0xffffff80
	s_nop 0
	global_load_lds_dwordx4 v132, s[48:49] offset:128
	s_waitcnt vmcnt(8)
	s_waitcnt lgkmcnt(0)
	s_barrier
	s_setprio 1
	s_waitcnt lgkmcnt(0)
	v_mfma_f32_16x16x32_bf16 v[92:95], v[146:149], v[188:191], v[92:95]
	v_mfma_f32_16x16x32_bf16 v[88:91], v[160:163], v[188:191], v[88:91]
	v_mfma_f32_16x16x32_bf16 v[84:87], v[146:149], v[196:199], v[84:87]
	v_mfma_f32_16x16x32_bf16 v[80:83], v[160:163], v[196:199], v[80:83]
	v_mfma_f32_16x16x32_bf16 v[76:79], v[146:149], v[204:207], v[76:79]
	v_mfma_f32_16x16x32_bf16 v[72:75], v[160:163], v[204:207], v[72:75]
	v_mfma_f32_16x16x32_bf16 v[68:71], v[146:149], v[212:215], v[68:71]
	v_mfma_f32_16x16x32_bf16 v[64:67], v[160:163], v[212:215], v[64:67]
	v_mfma_f32_16x16x32_bf16 v[92:95], v[150:153], v[192:195], v[92:95]
	v_mfma_f32_16x16x32_bf16 v[88:91], v[164:167], v[192:195], v[88:91]
	v_mfma_f32_16x16x32_bf16 v[84:87], v[150:153], v[200:203], v[84:87]
	v_mfma_f32_16x16x32_bf16 v[80:83], v[164:167], v[200:203], v[80:83]
	v_mfma_f32_16x16x32_bf16 v[76:79], v[150:153], v[208:211], v[76:79]
	v_mfma_f32_16x16x32_bf16 v[72:75], v[164:167], v[208:211], v[72:75]
	v_mfma_f32_16x16x32_bf16 v[68:71], v[150:153], v[216:219], v[68:71]
	v_mfma_f32_16x16x32_bf16 v[64:67], v[164:167], v[216:219], v[64:67]
	s_setprio 0
	s_setprio 1
	v_mfma_f32_16x16x32_bf16 v[28:31], v[172:175], v[188:191], v[28:31]
	v_mfma_f32_16x16x32_bf16 v[24:27], v[180:183], v[188:191], v[24:27]
	v_mfma_f32_16x16x32_bf16 v[20:23], v[172:175], v[196:199], v[20:23]
	v_mfma_f32_16x16x32_bf16 v[16:19], v[180:183], v[196:199], v[16:19]
	v_mfma_f32_16x16x32_bf16 v[12:15], v[172:175], v[204:207], v[12:15]
	v_mfma_f32_16x16x32_bf16 v[8:11], v[180:183], v[204:207], v[8:11]
	v_mfma_f32_16x16x32_bf16 v[4:7], v[172:175], v[212:215], v[4:7]
	v_mfma_f32_16x16x32_bf16 v[0:3], v[180:183], v[212:215], v[0:3]
	v_mfma_f32_16x16x32_bf16 v[28:31], v[176:179], v[192:195], v[28:31]
	v_mfma_f32_16x16x32_bf16 v[24:27], v[184:187], v[192:195], v[24:27]
	v_mfma_f32_16x16x32_bf16 v[20:23], v[176:179], v[200:203], v[20:23]
	v_mfma_f32_16x16x32_bf16 v[16:19], v[184:187], v[200:203], v[16:19]
	v_mfma_f32_16x16x32_bf16 v[12:15], v[176:179], v[208:211], v[12:15]
	v_mfma_f32_16x16x32_bf16 v[8:11], v[184:187], v[208:211], v[8:11]
	v_mfma_f32_16x16x32_bf16 v[4:7], v[176:179], v[216:219], v[4:7]
	v_mfma_f32_16x16x32_bf16 v[0:3], v[184:187], v[216:219], v[0:3]
	s_setprio 0
	s_barrier
	s_add_i32 s81, s81, 2
	s_add_u32 s30, s30, 0x100
	s_addc_u32 s31, s31, 0
	s_add_u32 s79, s79, 0x100
	s_addc_u32 s80, s80, 0
	s_cmp_gt_u32 s81, 29
	s_cbranch_scc0 .LBB0_393
	s_and_b64 vcc, exec, s[16:17]
	s_cbranch_vccz .LBB0_396
	s_barrier

; #define PG8_STAGE(bufoff, gbase, voff) do { _Pragma("unroll") for (int _i = 0; _i < 2; ++_i) \
;         __builtin_amdgcn_global_load_lds((const unsigned*)((const char*)(gbase) + (voff)[_i]), (PG8_LAS unsigned*)(lds + (bufoff) + ldsw + _i * 8192), 16, 0, 0); } while (0)
; #define PG8_LDA(dst, b, h) do { _Pragma("unroll") for (int m = 0; m < 4; ++m) _Pragma("unroll") for (int k = 0; k < 2; ++k) dst[m][k] = *(const PG8_LAS bf16x8*)(lds + PG8_SA(b, h) + aoff + m * 2048 + k * 1024); } while (0)
; #define PG8_LDB(dst, b, h) do { _Pragma("unroll") for (int n = 0; n < 2; ++n) _Pragma("unroll") for (int k = 0; k < 2; ++k) dst[n][k] = *(const PG8_LAS bf16x8*)(lds + PG8_SB(b, h) + boff + n * 2048 + k * 1024); } while (0)
; #define PG8_MMA(ai, bj, At, Bt) do { __builtin_amdgcn_s_setprio(1); _Pragma("unroll") for (int m = 0; m < 4; ++m) _Pragma("unroll") for (int n = 0; n < 2; ++n) _Pragma("unroll") for (int k = 0; k < 2; ++k) \
;         acc[ai][bj][m][n] = __builtin_amdgcn_mfma_f32_16x16x32_bf16(Bt[n][k], At[m][k], acc[ai][bj][m][n], 0, 0, 0); __builtin_amdgcn_s_setprio(0); } while (0)
; #define PG8_WAIT_V(n) asm volatile("s_waitcnt vmcnt(" #n ")" ::: "memory")
; #define PG8_WAIT_L(n) asm volatile("s_waitcnt lgkmcnt(" #n ")" ::: "memory")
; #define PG8_BAR __builtin_amdgcn_s_barrier()
; #define PG8_SCHED __builtin_amdgcn_sched_barrier(0)
; template <class Epi, class Sched, bool ALIGN_EPI = false, bool SP2 = false>
; __device__ __forceinline__ void gemm_phase(PG8_LAS unsigned char* lds, const Gemm g, const Sched& S, const Epi& E) {
;     ...
;             PG8_LDB(B0, 0, 0); PG8_LDB(B1, 0, 1); PG8_SCHED; PG8_LDA(At, 0, 0); PG8_STAGE(PG8_SA(1, 1), a1 + hstep, voffA);
;             PG8_WAIT_V(8); PG8_WAIT_L(0); PG8_BAR; PG8_MMA(0, 0, At, B0); PG8_MMA(0, 1, At, B1); PG8_BAR; PG8_SCHED;
;             PG8_LDA(At, 0, 1); PG8_STAGE(PG8_SB(0, 0), b2, voffB); PG8_STAGE(PG8_SB(0, 1), b2 + hstep, voffB); PG8_STAGE(PG8_SA(0, 0), a2, voffA);
;             PG8_WAIT_V(8); PG8_WAIT_L(0); PG8_BAR; PG8_MMA(1, 0, At, B0); PG8_MMA(1, 1, At, B1); PG8_BAR; PG8_SCHED;
.LBB0_523:
	ds_read_b128 v[154:157], v151
	ds_read_b128 v[158:161], v151 offset:1024
	ds_read_b128 v[162:165], v151 offset:2048
	ds_read_b128 v[166:169], v151 offset:3072
	ds_read_b128 v[174:177], v152
	ds_read_b128 v[178:181], v152 offset:1024
	ds_read_b128 v[182:185], v152 offset:2048
	ds_read_b128 v[186:189], v152 offset:3072
	s_add_u32 s30, s28, 0xfff80080
	s_addc_u32 s31, s29, -1
	s_cmp_eq_u32 s80, 28
	s_cselect_b32 s35, s21, s31
	s_cselect_b32 s34, s76, s30
	s_cselect_b32 s31, s19, s79
	s_cselect_b32 s30, s77, s78
	s_add_i32 m0, s27, 0xc000
	ds_read_b128 v[190:193], v153
	ds_read_b128 v[194:197], v153 offset:1024
	ds_read_b128 v[198:201], v153 offset:2048
	ds_read_b128 v[202:205], v153 offset:3072
	ds_read_b128 v[206:209], v153 offset:4096
	ds_read_b128 v[210:213], v153 offset:5120
	ds_read_b128 v[214:217], v153 offset:6144
	ds_read_b128 v[218:221], v153 offset:7168
	global_load_lds_dwordx4 v140, s[28:29]
	s_add_i32 m0, s27, 0xe000
	s_nop 0
	global_load_lds_dwordx4 v142, s[28:29]
	s_waitcnt vmcnt(8)
	s_waitcnt lgkmcnt(0)
	s_barrier
	s_setprio 1
	s_waitcnt lgkmcnt(0)
	v_mfma_f32_16x16x32_bf16 v[124:127], v[154:157], v[190:193], v[124:127]
	v_mfma_f32_16x16x32_bf16 v[120:123], v[162:165], v[190:193], v[120:123]
	v_mfma_f32_16x16x32_bf16 v[108:111], v[154:157], v[198:201], v[108:111]
	v_mfma_f32_16x16x32_bf16 v[104:107], v[162:165], v[198:201], v[104:107]
	v_mfma_f32_16x16x32_bf16 v[92:95], v[154:157], v[206:209], v[92:95]
	v_mfma_f32_16x16x32_bf16 v[88:91], v[162:165], v[206:209], v[88:91]
	v_mfma_f32_16x16x32_bf16 v[76:79], v[154:157], v[214:217], v[76:79]
	v_mfma_f32_16x16x32_bf16 v[72:75], v[162:165], v[214:217], v[72:75]
	v_mfma_f32_16x16x32_bf16 v[124:127], v[158:161], v[194:197], v[124:127]
	v_mfma_f32_16x16x32_bf16 v[120:123], v[166:169], v[194:197], v[120:123]
	v_mfma_f32_16x16x32_bf16 v[108:111], v[158:161], v[202:205], v[108:111]
	v_mfma_f32_16x16x32_bf16 v[104:107], v[166:169], v[202:205], v[104:107]
	v_mfma_f32_16x16x32_bf16 v[92:95], v[158:161], v[210:213], v[92:95]
	v_mfma_f32_16x16x32_bf16 v[88:91], v[166:169], v[210:213], v[88:91]
	v_mfma_f32_16x16x32_bf16 v[76:79], v[158:161], v[218:221], v[76:79]
	v_mfma_f32_16x16x32_bf16 v[72:75], v[166:169], v[218:221], v[72:75]
	s_setprio 0
	s_setprio 1
	v_mfma_f32_16x16x32_bf16 v[116:119], v[174:177], v[190:193], v[116:119]
	v_mfma_f32_16x16x32_bf16 v[112:115], v[182:185], v[190:193], v[112:115]
	v_mfma_f32_16x16x32_bf16 v[100:103], v[174:177], v[198:201], v[100:103]
	v_mfma_f32_16x16x32_bf16 v[96:99], v[182:185], v[198:201], v[96:99]
	v_mfma_f32_16x16x32_bf16 v[84:87], v[174:177], v[206:209], v[84:87]
	v_mfma_f32_16x16x32_bf16 v[80:83], v[182:185], v[206:209], v[80:83]
	v_mfma_f32_16x16x32_bf16 v[68:71], v[174:177], v[214:217], v[68:71]
	v_mfma_f32_16x16x32_bf16 v[64:67], v[182:185], v[214:217], v[64:67]
	v_mfma_f32_16x16x32_bf16 v[116:119], v[178:181], v[194:197], v[116:119]
	v_mfma_f32_16x16x32_bf16 v[112:115], v[186:189], v[194:197], v[112:115]
	v_mfma_f32_16x16x32_bf16 v[100:103], v[178:181], v[202:205], v[100:103]
	v_mfma_f32_16x16x32_bf16 v[96:99], v[186:189], v[202:205], v[96:99]
	v_mfma_f32_16x16x32_bf16 v[84:87], v[178:181], v[210:213], v[84:87]
	v_mfma_f32_16x16x32_bf16 v[80:83], v[186:189], v[210:213], v[80:83]
	v_mfma_f32_16x16x32_bf16 v[68:71], v[178:181], v[218:221], v[68:71]
	v_mfma_f32_16x16x32_bf16 v[64:67], v[186:189], v[218:221], v[64:67]
	s_setprio 0
	s_barrier
	s_add_i32 s36, s72, s3
	s_mov_b32 m0, s36
	ds_read_b128 v[190:193], v153 offset:16384
	ds_read_b128 v[194:197], v153 offset:17408
	ds_read_b128 v[198:201], v153 offset:18432
	ds_read_b128 v[202:205], v153 offset:19456
	ds_read_b128 v[206:209], v153 offset:20480
	ds_read_b128 v[210:213], v153 offset:21504
	ds_read_b128 v[214:217], v153 offset:22528
	ds_read_b128 v[218:221], v153 offset:23552
	global_load_lds_dwordx4 v132, s[30:31]
	s_add_i32 m0, s36, 0x2000
	s_add_u32 s36, s30, 0x80000
	s_addc_u32 s37, s31, 0
	s_add_i32 s58, s73, s3
	global_load_lds_dwordx4 v128, s[30:31]
	s_mov_b32 m0, s58
	v_lshl_add_u64 v[226:227], s[34:35], 0, v[130:131]
	global_load_lds_dwordx4 v132, s[36:37]
	s_add_i32 m0, s58, 0x2000
	s_nop 0
	global_load_lds_dwordx4 v128, s[36:37]
	v_lshl_add_u64 v[224:225], s[34:35], 0, v[134:135]
	s_mov_b32 m0, s27
	s_nop 0
	global_load_lds_dwordx4 v134, s[34:35]
	s_mov_b32 m0, s49
	s_nop 0
	global_load_lds_dwordx4 v130, s[34:35]
	s_waitcnt vmcnt(8)
	s_waitcnt lgkmcnt(0)
	s_barrier
	s_setprio 1
	s_waitcnt lgkmcnt(0)
	v_mfma_f32_16x16x32_bf16 v[60:63], v[154:157], v[190:193], v[60:63]
	v_mfma_f32_16x16x32_bf16 v[56:59], v[162:165], v[190:193], v[56:59]
	v_mfma_f32_16x16x32_bf16 v[44:47], v[154:157], v[198:201], v[44:47]
	v_mfma_f32_16x16x32_bf16 v[40:43], v[162:165], v[198:201], v[40:43]
	v_mfma_f32_16x16x32_bf16 v[28:31], v[154:157], v[206:209], v[28:31]
	v_mfma_f32_16x16x32_bf16 v[24:27], v[162:165], v[206:209], v[24:27]
	v_mfma_f32_16x16x32_bf16 v[12:15], v[154:157], v[214:217], v[12:15]
	v_mfma_f32_16x16x32_bf16 v[8:11], v[162:165], v[214:217], v[8:11]
	v_mfma_f32_16x16x32_bf16 v[60:63], v[158:161], v[194:197], v[60:63]
	v_mfma_f32_16x16x32_bf16 v[56:59], v[166:169], v[194:197], v[56:59]
	v_mfma_f32_16x16x32_bf16 v[44:47], v[158:161], v[202:205], v[44:47]
	v_mfma_f32_16x16x32_bf16 v[40:43], v[166:169], v[202:205], v[40:43]
	v_mfma_f32_16x16x32_bf16 v[28:31], v[158:161], v[210:213], v[28:31]
	v_mfma_f32_16x16x32_bf16 v[24:27], v[166:169], v[210:213], v[24:27]
	v_mfma_f32_16x16x32_bf16 v[12:15], v[158:161], v[218:221], v[12:15]
	v_mfma_f32_16x16x32_bf16 v[8:11], v[166:169], v[218:221], v[8:11]
	s_setprio 0
	s_setprio 1
	v_mfma_f32_16x16x32_bf16 v[52:55], v[174:177], v[190:193], v[52:55]
	v_mfma_f32_16x16x32_bf16 v[48:51], v[182:185], v[190:193], v[48:51]
	v_mfma_f32_16x16x32_bf16 v[36:39], v[174:177], v[198:201], v[36:39]
	v_mfma_f32_16x16x32_bf16 v[32:35], v[182:185], v[198:201], v[32:35]
	v_mfma_f32_16x16x32_bf16 v[20:23], v[174:177], v[206:209], v[20:23]
	v_mfma_f32_16x16x32_bf16 v[16:19], v[182:185], v[206:209], v[16:19]
	v_mfma_f32_16x16x32_bf16 v[4:7], v[174:177], v[214:217], v[4:7]
	v_mfma_f32_16x16x32_bf16 v[0:3], v[182:185], v[214:217], v[0:3]
	v_mfma_f32_16x16x32_bf16 v[52:55], v[178:181], v[194:197], v[52:55]
	v_mfma_f32_16x16x32_bf16 v[48:51], v[186:189], v[194:197], v[48:51]
	v_mfma_f32_16x16x32_bf16 v[36:39], v[178:181], v[202:205], v[36:39]
	v_mfma_f32_16x16x32_bf16 v[32:35], v[186:189], v[202:205], v[32:35]
	v_mfma_f32_16x16x32_bf16 v[20:23], v[178:181], v[210:213], v[20:23]
	v_mfma_f32_16x16x32_bf16 v[16:19], v[186:189], v[210:213], v[16:19]
	v_mfma_f32_16x16x32_bf16 v[4:7], v[178:181], v[218:221], v[4:7]
	v_mfma_f32_16x16x32_bf16 v[0:3], v[186:189], v[218:221], v[0:3]
	s_setprio 0
	s_barrier
; #define PG8_STAGE(bufoff, gbase, voff) do { _Pragma("unroll") for (int _i = 0; _i < 2; ++_i) \
;         __builtin_amdgcn_global_load_lds((const unsigned*)((const char*)(gbase) + (voff)[_i]), (PG8_LAS unsigned*)(lds + (bufoff) + ldsw + _i * 8192), 16, 0, 0); } while (0)
; #define PG8_LDA(dst, b, h) do { _Pragma("unroll") for (int m = 0; m < 4; ++m) _Pragma("unroll") for (int k = 0; k < 2; ++k) dst[m][k] = *(const PG8_LAS bf16x8*)(lds + PG8_SA(b, h) + aoff + m * 2048 + k * 1024); } while (0)
; #define PG8_LDB(dst, b, h) do { _Pragma("unroll") for (int n = 0; n < 2; ++n) _Pragma("unroll") for (int k = 0; k < 2; ++k) dst[n][k] = *(const PG8_LAS bf16x8*)(lds + PG8_SB(b, h) + boff + n * 2048 + k * 1024); } while (0)
; template <class Epi, class Sched, bool ALIGN_EPI = false, bool SP2 = false>
; __device__ __forceinline__ void gemm_phase(PG8_LAS unsigned char* lds, const Gemm g, const Sched& S, const Epi& E) {
;     ...
;         for (int t = 0; t < nt; t += 2) {
;             const bool last = (t == nt - 2);
;             const char* a1 = cA + (size_t)(t + 1) * kstep;
;             const char* a2 = last ? nA : cA + (size_t)(t + 2) * kstep; const char* b2 = last ? nB : cB + (size_t)(t + 2) * kstep;
;             const char* a3 = a2 + kstep; const char* b3 = b2 + kstep;
;             if (last && has_next) S.a_ready(nxt);
;             if constexpr (SP2) {
;             PG8_LDB(B0, 0, 0); PG8_LDB(B1, 0, 1); PG8_SCHED; PG8_LDA(At, 0, 0); PG8_STAGE(PG8_SA(1, 1), a1 + hstep, voffA);
;             PG8_WAIT_V(8); PG8_WAIT_L(0); PG8_BAR; PG8_MMA(0, 0, At, B0); PG8_MMA(0, 1, At, B1); PG8_BAR; PG8_SCHED;
;             PG8_LDA(At, 0, 1); PG8_STAGE(PG8_SB(0, 0), b2, voffB); PG8_STAGE(PG8_SB(0, 1), b2 + hstep, voffB); PG8_STAGE(PG8_SA(0, 0), a2, voffA);
;             PG8_WAIT_V(8); PG8_WAIT_L(0); PG8_BAR; PG8_MMA(1, 0, At, B0); PG8_MMA(1, 1, At, B1); PG8_BAR; PG8_SCHED;
;             PG8_LDB(B0, 1, 0); PG8_LDB(B1, 1, 1); PG8_SCHED; PG8_LDA(At, 1, 0); PG8_STAGE(PG8_SA(0, 1), a2 + hstep, voffA);
;             PG8_WAIT_V(8); PG8_WAIT_L(0); PG8_BAR; PG8_MMA(0, 0, At, B0); PG8_MMA(0, 1, At, B1); PG8_BAR; PG8_SCHED;
;             PG8_LDA(At, 1, 1); PG8_STAGE(PG8_SB(1, 0), b3, voffB); PG8_STAGE(PG8_SB(1, 1), b3 + hstep, voffB); PG8_STAGE(PG8_SA(1, 0), a3, voffA);
;             PG8_WAIT_V(8); PG8_WAIT_L(0); PG8_BAR; PG8_MMA(1, 0, At, B0); PG8_MMA(1, 1, At, B1); PG8_BAR; PG8_SCHED;
	s_add_i32 s36, 0, 0x18000
	s_add_i32 s37, 0, 0x1c000
	v_add_u32_e32 v166, s36, v139
	v_add_u32_e32 v171, s37, v139
	ds_read_b128 v[154:157], v166
	ds_read_b128 v[158:161], v166 offset:1024
	ds_read_b128 v[162:165], v166 offset:2048
	ds_read_b128 v[166:169], v166 offset:3072
	ds_read_b128 v[174:177], v171
	ds_read_b128 v[178:181], v171 offset:1024
	ds_read_b128 v[182:185], v171 offset:2048
	ds_read_b128 v[186:189], v171 offset:3072
	s_add_u32 s34, s34, 0x80000
	s_addc_u32 s35, s35, 0
	s_mov_b32 m0, s50
	ds_read_b128 v[190:193], v153 offset:32768
	ds_read_b128 v[194:197], v153 offset:33792
	ds_read_b128 v[198:201], v153 offset:34816
	ds_read_b128 v[202:205], v153 offset:35840
	ds_read_b128 v[206:209], v153 offset:36864
	ds_read_b128 v[210:213], v153 offset:37888
	ds_read_b128 v[214:217], v153 offset:38912
	ds_read_b128 v[218:221], v153 offset:39936
	global_load_lds_dwordx4 v134, s[34:35]
	s_mov_b32 m0, s51
	s_nop 0
	global_load_lds_dwordx4 v130, s[34:35]
	s_waitcnt vmcnt(8)
	s_waitcnt lgkmcnt(0)
	s_barrier
	s_setprio 1
	s_waitcnt lgkmcnt(0)
	v_mfma_f32_16x16x32_bf16 v[124:127], v[154:157], v[190:193], v[124:127]
	v_mfma_f32_16x16x32_bf16 v[120:123], v[162:165], v[190:193], v[120:123]
	v_mfma_f32_16x16x32_bf16 v[108:111], v[154:157], v[198:201], v[108:111]
	v_mfma_f32_16x16x32_bf16 v[104:107], v[162:165], v[198:201], v[104:107]
	v_mfma_f32_16x16x32_bf16 v[92:95], v[154:157], v[206:209], v[92:95]
	v_mfma_f32_16x16x32_bf16 v[88:91], v[162:165], v[206:209], v[88:91]
	v_mfma_f32_16x16x32_bf16 v[76:79], v[154:157], v[214:217], v[76:79]
	v_mfma_f32_16x16x32_bf16 v[72:75], v[162:165], v[214:217], v[72:75]
	v_mfma_f32_16x16x32_bf16 v[124:127], v[158:161], v[194:197], v[124:127]
	v_mfma_f32_16x16x32_bf16 v[120:123], v[166:169], v[194:197], v[120:123]
	v_mfma_f32_16x16x32_bf16 v[108:111], v[158:161], v[202:205], v[108:111]
	v_mfma_f32_16x16x32_bf16 v[104:107], v[166:169], v[202:205], v[104:107]
	v_mfma_f32_16x16x32_bf16 v[92:95], v[158:161], v[210:213], v[92:95]
	v_mfma_f32_16x16x32_bf16 v[88:91], v[166:169], v[210:213], v[88:91]
	v_mfma_f32_16x16x32_bf16 v[76:79], v[158:161], v[218:221], v[76:79]
	v_mfma_f32_16x16x32_bf16 v[72:75], v[166:169], v[218:221], v[72:75]
	s_setprio 0
	s_setprio 1
	v_mfma_f32_16x16x32_bf16 v[116:119], v[174:177], v[190:193], v[116:119]
	v_mfma_f32_16x16x32_bf16 v[112:115], v[182:185], v[190:193], v[112:115]
	v_mfma_f32_16x16x32_bf16 v[100:103], v[174:177], v[198:201], v[100:103]
	v_mfma_f32_16x16x32_bf16 v[96:99], v[182:185], v[198:201], v[96:99]
	v_mfma_f32_16x16x32_bf16 v[84:87], v[174:177], v[206:209], v[84:87]
	v_mfma_f32_16x16x32_bf16 v[80:83], v[182:185], v[206:209], v[80:83]
	v_mfma_f32_16x16x32_bf16 v[68:71], v[174:177], v[214:217], v[68:71]
	v_mfma_f32_16x16x32_bf16 v[64:67], v[182:185], v[214:217], v[64:67]
	v_mfma_f32_16x16x32_bf16 v[116:119], v[178:181], v[194:197], v[116:119]
	v_mfma_f32_16x16x32_bf16 v[112:115], v[186:189], v[194:197], v[112:115]
	v_mfma_f32_16x16x32_bf16 v[100:103], v[178:181], v[202:205], v[100:103]
	v_mfma_f32_16x16x32_bf16 v[96:99], v[186:189], v[202:205], v[96:99]
	v_mfma_f32_16x16x32_bf16 v[84:87], v[178:181], v[210:213], v[84:87]
	v_mfma_f32_16x16x32_bf16 v[80:83], v[186:189], v[210:213], v[80:83]
	v_mfma_f32_16x16x32_bf16 v[68:71], v[178:181], v[218:221], v[68:71]
	v_mfma_f32_16x16x32_bf16 v[64:67], v[186:189], v[218:221], v[64:67]
	s_setprio 0
	s_barrier
	s_add_i32 s34, s36, s3
	s_add_i32 m0, s34, 0xffffff80
	ds_read_b128 v[190:193], v153 offset:49152
	ds_read_b128 v[194:197], v153 offset:50176
	ds_read_b128 v[198:201], v153 offset:51200
	ds_read_b128 v[202:205], v153 offset:52224
	ds_read_b128 v[206:209], v153 offset:53248
	ds_read_b128 v[210:213], v153 offset:54272
	ds_read_b128 v[214:217], v153 offset:55296
	ds_read_b128 v[218:221], v153 offset:56320
	global_load_lds_dwordx4 v132, s[30:31] offset:128
	s_add_i32 m0, s34, 0x1f80
	s_nop 0
	global_load_lds_dwordx4 v128, s[30:31] offset:128
	s_add_u32 s30, s30, 0x80080
	s_addc_u32 s31, s31, 0
	s_add_i32 s34, s37, s3
	s_mov_b32 m0, s34
	s_nop 0
	global_load_lds_dwordx4 v132, s[30:31]
	s_add_i32 m0, s34, 0x2000
	s_nop 0
	global_load_lds_dwordx4 v128, s[30:31]
	v_lshl_add_u64 v[148:149], v[224:225], 0, s[14:15]
	s_mov_b32 m0, s53
	s_nop 0
	global_load_lds_dwordx4 v[148:149], off
	v_lshl_add_u64 v[148:149], v[226:227], 0, s[14:15]
	s_mov_b32 m0, s54
	s_nop 0
	global_load_lds_dwordx4 v[148:149], off
	s_waitcnt vmcnt(8)
	s_waitcnt lgkmcnt(0)
	s_barrier
	s_setprio 1
	s_waitcnt lgkmcnt(0)
	v_mfma_f32_16x16x32_bf16 v[60:63], v[154:157], v[190:193], v[60:63]
	v_mfma_f32_16x16x32_bf16 v[56:59], v[162:165], v[190:193], v[56:59]
	v_mfma_f32_16x16x32_bf16 v[44:47], v[154:157], v[198:201], v[44:47]
	v_mfma_f32_16x16x32_bf16 v[40:43], v[162:165], v[198:201], v[40:43]
	v_mfma_f32_16x16x32_bf16 v[28:31], v[154:157], v[206:209], v[28:31]
	v_mfma_f32_16x16x32_bf16 v[24:27], v[162:165], v[206:209], v[24:27]
	v_mfma_f32_16x16x32_bf16 v[12:15], v[154:157], v[214:217], v[12:15]
	v_mfma_f32_16x16x32_bf16 v[8:11], v[162:165], v[214:217], v[8:11]
	v_mfma_f32_16x16x32_bf16 v[60:63], v[158:161], v[194:197], v[60:63]
	v_mfma_f32_16x16x32_bf16 v[56:59], v[166:169], v[194:197], v[56:59]
	v_mfma_f32_16x16x32_bf16 v[44:47], v[158:161], v[202:205], v[44:47]
	v_mfma_f32_16x16x32_bf16 v[40:43], v[166:169], v[202:205], v[40:43]
	v_mfma_f32_16x16x32_bf16 v[28:31], v[158:161], v[210:213], v[28:31]
	v_mfma_f32_16x16x32_bf16 v[24:27], v[166:169], v[210:213], v[24:27]
	v_mfma_f32_16x16x32_bf16 v[12:15], v[158:161], v[218:221], v[12:15]
	v_mfma_f32_16x16x32_bf16 v[8:11], v[166:169], v[218:221], v[8:11]
	s_setprio 0
	s_setprio 1
	v_mfma_f32_16x16x32_bf16 v[52:55], v[174:177], v[190:193], v[52:55]
	v_mfma_f32_16x16x32_bf16 v[48:51], v[182:185], v[190:193], v[48:51]
	v_mfma_f32_16x16x32_bf16 v[36:39], v[174:177], v[198:201], v[36:39]
	v_mfma_f32_16x16x32_bf16 v[32:35], v[182:185], v[198:201], v[32:35]
	v_mfma_f32_16x16x32_bf16 v[20:23], v[174:177], v[206:209], v[20:23]
	v_mfma_f32_16x16x32_bf16 v[16:19], v[182:185], v[206:209], v[16:19]
	v_mfma_f32_16x16x32_bf16 v[4:7], v[174:177], v[214:217], v[4:7]
	v_mfma_f32_16x16x32_bf16 v[0:3], v[182:185], v[214:217], v[0:3]
	v_mfma_f32_16x16x32_bf16 v[52:55], v[178:181], v[194:197], v[52:55]
	v_mfma_f32_16x16x32_bf16 v[48:51], v[186:189], v[194:197], v[48:51]
	v_mfma_f32_16x16x32_bf16 v[36:39], v[178:181], v[202:205], v[36:39]
	v_mfma_f32_16x16x32_bf16 v[32:35], v[186:189], v[202:205], v[32:35]
	v_mfma_f32_16x16x32_bf16 v[20:23], v[178:181], v[210:213], v[20:23]
	v_mfma_f32_16x16x32_bf16 v[16:19], v[186:189], v[210:213], v[16:19]
	v_mfma_f32_16x16x32_bf16 v[4:7], v[178:181], v[218:221], v[4:7]
	v_mfma_f32_16x16x32_bf16 v[0:3], v[186:189], v[218:221], v[0:3]
	s_setprio 0
	s_barrier
	s_add_i32 s80, s80, 2
	s_add_u32 s28, s28, 0x100
	s_addc_u32 s29, s29, 0
	s_add_u32 s78, s78, 0x100
	s_addc_u32 s79, s79, 0
	s_cmp_gt_u32 s80, 29
	s_cbranch_scc0 .LBB0_523
	s_and_b64 vcc, exec, s[16:17]
	s_cbranch_vccz .LBB0_526
	s_barrier

; #define PG8_STAGE(bufoff, gbase, voff) do { _Pragma("unroll") for (int _i = 0; _i < 2; ++_i) \
;         __builtin_amdgcn_global_load_lds((const unsigned*)((const char*)(gbase) + (voff)[_i]), (PG8_LAS unsigned*)(lds + (bufoff) + ldsw + _i * 8192), 16, 0, 0); } while (0)
; #define PG8_LDA(dst, b, h) do { _Pragma("unroll") for (int m = 0; m < 4; ++m) _Pragma("unroll") for (int k = 0; k < 2; ++k) dst[m][k] = *(const PG8_LAS bf16x8*)(lds + PG8_SA(b, h) + aoff + m * 2048 + k * 1024); } while (0)
; #define PG8_LDB(dst, b, h) do { _Pragma("unroll") for (int n = 0; n < 2; ++n) _Pragma("unroll") for (int k = 0; k < 2; ++k) dst[n][k] = *(const PG8_LAS bf16x8*)(lds + PG8_SB(b, h) + boff + n * 2048 + k * 1024); } while (0)
; #define PG8_MMA(ai, bj, At, Bt) do { __builtin_amdgcn_s_setprio(1); _Pragma("unroll") for (int m = 0; m < 4; ++m) _Pragma("unroll") for (int n = 0; n < 2; ++n) _Pragma("unroll") for (int k = 0; k < 2; ++k) \
;         acc[ai][bj][m][n] = __builtin_amdgcn_mfma_f32_16x16x32_bf16(Bt[n][k], At[m][k], acc[ai][bj][m][n], 0, 0, 0); __builtin_amdgcn_s_setprio(0); } while (0)
; #define PG8_WAIT_V(n) asm volatile("s_waitcnt vmcnt(" #n ")" ::: "memory")
; #define PG8_WAIT_L(n) asm volatile("s_waitcnt lgkmcnt(" #n ")" ::: "memory")
; #define PG8_BAR __builtin_amdgcn_s_barrier()
; #define PG8_SCHED __builtin_amdgcn_sched_barrier(0)
; template <class Epi, class Sched, bool ALIGN_EPI = false, bool SP2 = false>
; __device__ __forceinline__ void gemm_phase(PG8_LAS unsigned char* lds, const Gemm g, const Sched& S, const Epi& E) {
;     ...
;             PG8_LDB(B0, 0, 0); PG8_LDB(B1, 0, 1); PG8_SCHED; PG8_LDA(At, 0, 0); PG8_STAGE(PG8_SA(1, 1), a1 + hstep, voffA);
;             PG8_WAIT_V(8); PG8_WAIT_L(0); PG8_BAR; PG8_MMA(0, 0, At, B0); PG8_MMA(0, 1, At, B1); PG8_BAR; PG8_SCHED;
;             PG8_LDA(At, 0, 1); PG8_STAGE(PG8_SB(0, 0), b2, voffB); PG8_STAGE(PG8_SB(0, 1), b2 + hstep, voffB); PG8_STAGE(PG8_SA(0, 0), a2, voffA);
;             PG8_WAIT_V(8); PG8_WAIT_L(0); PG8_BAR; PG8_MMA(1, 0, At, B0); PG8_MMA(1, 1, At, B1); PG8_BAR; PG8_SCHED;
.LBB0_606:
	ds_read_b128 v[150:153], v158
	ds_read_b128 v[154:157], v158 offset:1024
	ds_read_b128 v[162:165], v158 offset:2048
	ds_read_b128 v[166:169], v158 offset:3072
	ds_read_b128 v[174:177], v159
	ds_read_b128 v[178:181], v159 offset:1024
	ds_read_b128 v[182:185], v159 offset:2048
	ds_read_b128 v[186:189], v159 offset:3072
	s_add_u32 s26, s24, 0xffea0080
	s_addc_u32 s27, s25, -1
	s_cmpk_eq_i32 s73, 0x54
	s_cselect_b32 s29, s7, s27
	s_cselect_b32 s28, s6, s26
	s_cselect_b32 s27, s23, s72
	s_cselect_b32 s26, s22, s67
	s_add_i32 m0, s30, 0xc000
	ds_read_b128 v[190:193], v160
	ds_read_b128 v[194:197], v160 offset:1024
	ds_read_b128 v[198:201], v160 offset:2048
	ds_read_b128 v[202:205], v160 offset:3072
	ds_read_b128 v[206:209], v160 offset:4096
	ds_read_b128 v[210:213], v160 offset:5120
	ds_read_b128 v[214:217], v160 offset:6144
	ds_read_b128 v[218:221], v160 offset:7168
	global_load_lds_dwordx4 v142, s[24:25]
	s_add_i32 m0, s30, 0xe000
	s_nop 0
	global_load_lds_dwordx4 v144, s[24:25]
	s_waitcnt vmcnt(8)
	s_waitcnt lgkmcnt(0)
	s_barrier
	s_setprio 1
	s_waitcnt lgkmcnt(0)
	v_mfma_f32_16x16x32_bf16 v[124:127], v[150:153], v[190:193], v[124:127]
	v_mfma_f32_16x16x32_bf16 v[120:123], v[162:165], v[190:193], v[120:123]
	v_mfma_f32_16x16x32_bf16 v[116:119], v[150:153], v[198:201], v[116:119]
	v_mfma_f32_16x16x32_bf16 v[112:115], v[162:165], v[198:201], v[112:115]
	v_mfma_f32_16x16x32_bf16 v[108:111], v[150:153], v[206:209], v[108:111]
	v_mfma_f32_16x16x32_bf16 v[104:107], v[162:165], v[206:209], v[104:107]
	v_mfma_f32_16x16x32_bf16 v[100:103], v[150:153], v[214:217], v[100:103]
	v_mfma_f32_16x16x32_bf16 v[96:99], v[162:165], v[214:217], v[96:99]
	v_mfma_f32_16x16x32_bf16 v[124:127], v[154:157], v[194:197], v[124:127]
	v_mfma_f32_16x16x32_bf16 v[120:123], v[166:169], v[194:197], v[120:123]
	v_mfma_f32_16x16x32_bf16 v[116:119], v[154:157], v[202:205], v[116:119]
	v_mfma_f32_16x16x32_bf16 v[112:115], v[166:169], v[202:205], v[112:115]
	v_mfma_f32_16x16x32_bf16 v[108:111], v[154:157], v[210:213], v[108:111]
	v_mfma_f32_16x16x32_bf16 v[104:107], v[166:169], v[210:213], v[104:107]
	v_mfma_f32_16x16x32_bf16 v[100:103], v[154:157], v[218:221], v[100:103]
	v_mfma_f32_16x16x32_bf16 v[96:99], v[166:169], v[218:221], v[96:99]
	s_setprio 0
	s_setprio 1
	v_mfma_f32_16x16x32_bf16 v[60:63], v[174:177], v[190:193], v[60:63]
	v_mfma_f32_16x16x32_bf16 v[56:59], v[182:185], v[190:193], v[56:59]
	v_mfma_f32_16x16x32_bf16 v[52:55], v[174:177], v[198:201], v[52:55]
	v_mfma_f32_16x16x32_bf16 v[48:51], v[182:185], v[198:201], v[48:51]
	v_mfma_f32_16x16x32_bf16 v[44:47], v[174:177], v[206:209], v[44:47]
	v_mfma_f32_16x16x32_bf16 v[40:43], v[182:185], v[206:209], v[40:43]
	v_mfma_f32_16x16x32_bf16 v[36:39], v[174:177], v[214:217], v[36:39]
	v_mfma_f32_16x16x32_bf16 v[32:35], v[182:185], v[214:217], v[32:35]
	v_mfma_f32_16x16x32_bf16 v[60:63], v[178:181], v[194:197], v[60:63]
	v_mfma_f32_16x16x32_bf16 v[56:59], v[186:189], v[194:197], v[56:59]
	v_mfma_f32_16x16x32_bf16 v[52:55], v[178:181], v[202:205], v[52:55]
	v_mfma_f32_16x16x32_bf16 v[48:51], v[186:189], v[202:205], v[48:51]
	v_mfma_f32_16x16x32_bf16 v[44:47], v[178:181], v[210:213], v[44:47]
	v_mfma_f32_16x16x32_bf16 v[40:43], v[186:189], v[210:213], v[40:43]
	v_mfma_f32_16x16x32_bf16 v[36:39], v[178:181], v[218:221], v[36:39]
	v_mfma_f32_16x16x32_bf16 v[32:35], v[186:189], v[218:221], v[32:35]
	s_setprio 0
	s_barrier
	s_add_i32 s36, s52, s21
	s_mov_b32 m0, s36
	ds_read_b128 v[190:193], v160 offset:16384
	ds_read_b128 v[194:197], v160 offset:17408
	ds_read_b128 v[198:201], v160 offset:18432
	ds_read_b128 v[202:205], v160 offset:19456
	ds_read_b128 v[206:209], v160 offset:20480
	ds_read_b128 v[210:213], v160 offset:21504
	ds_read_b128 v[214:217], v160 offset:22528
	ds_read_b128 v[218:221], v160 offset:23552
	global_load_lds_dwordx4 v130, s[26:27]
	s_add_i32 m0, s36, 0x2000
	s_add_u32 s36, s26, 0x160000
	s_addc_u32 s37, s27, 0
	s_add_i32 s58, s53, s21
	global_load_lds_dwordx4 v134, s[26:27]
	s_mov_b32 m0, s58
	v_lshl_add_u64 v[228:229], s[28:29], 0, v[132:133]
	global_load_lds_dwordx4 v130, s[36:37]
	s_add_i32 m0, s58, 0x2000
	s_nop 0
	global_load_lds_dwordx4 v134, s[36:37]
	v_lshl_add_u64 v[226:227], s[28:29], 0, v[128:129]
	s_mov_b32 m0, s30
	s_nop 0
	global_load_lds_dwordx4 v128, s[28:29]
	s_mov_b32 m0, s31
	s_nop 0
	global_load_lds_dwordx4 v132, s[28:29]
	s_waitcnt vmcnt(8)
	s_waitcnt lgkmcnt(0)
	s_barrier
	s_setprio 1
	s_waitcnt lgkmcnt(0)
	v_mfma_f32_16x16x32_bf16 v[92:95], v[150:153], v[190:193], v[92:95]
	v_mfma_f32_16x16x32_bf16 v[88:91], v[162:165], v[190:193], v[88:91]
	v_mfma_f32_16x16x32_bf16 v[84:87], v[150:153], v[198:201], v[84:87]
	v_mfma_f32_16x16x32_bf16 v[80:83], v[162:165], v[198:201], v[80:83]
	v_mfma_f32_16x16x32_bf16 v[76:79], v[150:153], v[206:209], v[76:79]
	v_mfma_f32_16x16x32_bf16 v[72:75], v[162:165], v[206:209], v[72:75]
	v_mfma_f32_16x16x32_bf16 v[68:71], v[150:153], v[214:217], v[68:71]
	v_mfma_f32_16x16x32_bf16 v[64:67], v[162:165], v[214:217], v[64:67]
	v_mfma_f32_16x16x32_bf16 v[92:95], v[154:157], v[194:197], v[92:95]
	v_mfma_f32_16x16x32_bf16 v[88:91], v[166:169], v[194:197], v[88:91]
	v_mfma_f32_16x16x32_bf16 v[84:87], v[154:157], v[202:205], v[84:87]
	v_mfma_f32_16x16x32_bf16 v[80:83], v[166:169], v[202:205], v[80:83]
	v_mfma_f32_16x16x32_bf16 v[76:79], v[154:157], v[210:213], v[76:79]
	v_mfma_f32_16x16x32_bf16 v[72:75], v[166:169], v[210:213], v[72:75]
	v_mfma_f32_16x16x32_bf16 v[68:71], v[154:157], v[218:221], v[68:71]
	v_mfma_f32_16x16x32_bf16 v[64:67], v[166:169], v[218:221], v[64:67]
	s_setprio 0
	s_setprio 1
	v_mfma_f32_16x16x32_bf16 v[28:31], v[174:177], v[190:193], v[28:31]
	v_mfma_f32_16x16x32_bf16 v[24:27], v[182:185], v[190:193], v[24:27]
	v_mfma_f32_16x16x32_bf16 v[20:23], v[174:177], v[198:201], v[20:23]
	v_mfma_f32_16x16x32_bf16 v[16:19], v[182:185], v[198:201], v[16:19]
	v_mfma_f32_16x16x32_bf16 v[12:15], v[174:177], v[206:209], v[12:15]
	v_mfma_f32_16x16x32_bf16 v[8:11], v[182:185], v[206:209], v[8:11]
	v_mfma_f32_16x16x32_bf16 v[4:7], v[174:177], v[214:217], v[4:7]
	v_mfma_f32_16x16x32_bf16 v[0:3], v[182:185], v[214:217], v[0:3]
	v_mfma_f32_16x16x32_bf16 v[28:31], v[178:181], v[194:197], v[28:31]
	v_mfma_f32_16x16x32_bf16 v[24:27], v[186:189], v[194:197], v[24:27]
	v_mfma_f32_16x16x32_bf16 v[20:23], v[178:181], v[202:205], v[20:23]
	v_mfma_f32_16x16x32_bf16 v[16:19], v[186:189], v[202:205], v[16:19]
	v_mfma_f32_16x16x32_bf16 v[12:15], v[178:181], v[210:213], v[12:15]
	v_mfma_f32_16x16x32_bf16 v[8:11], v[186:189], v[210:213], v[8:11]
	v_mfma_f32_16x16x32_bf16 v[4:7], v[178:181], v[218:221], v[4:7]
	v_mfma_f32_16x16x32_bf16 v[0:3], v[186:189], v[218:221], v[0:3]
	s_setprio 0
	s_barrier
; #define PG8_STAGE(bufoff, gbase, voff) do { _Pragma("unroll") for (int _i = 0; _i < 2; ++_i) \
;         __builtin_amdgcn_global_load_lds((const unsigned*)((const char*)(gbase) + (voff)[_i]), (PG8_LAS unsigned*)(lds + (bufoff) + ldsw + _i * 8192), 16, 0, 0); } while (0)
; #define PG8_LDA(dst, b, h) do { _Pragma("unroll") for (int m = 0; m < 4; ++m) _Pragma("unroll") for (int k = 0; k < 2; ++k) dst[m][k] = *(const PG8_LAS bf16x8*)(lds + PG8_SA(b, h) + aoff + m * 2048 + k * 1024); } while (0)
; #define PG8_LDB(dst, b, h) do { _Pragma("unroll") for (int n = 0; n < 2; ++n) _Pragma("unroll") for (int k = 0; k < 2; ++k) dst[n][k] = *(const PG8_LAS bf16x8*)(lds + PG8_SB(b, h) + boff + n * 2048 + k * 1024); } while (0)
; template <class Epi, class Sched, bool ALIGN_EPI = false, bool SP2 = false>
; __device__ __forceinline__ void gemm_phase(PG8_LAS unsigned char* lds, const Gemm g, const Sched& S, const Epi& E) {
;     ...
;         for (int t = 0; t < nt; t += 2) {
;             const bool last = (t == nt - 2);
;             const char* a1 = cA + (size_t)(t + 1) * kstep;
;             const char* a2 = last ? nA : cA + (size_t)(t + 2) * kstep; const char* b2 = last ? nB : cB + (size_t)(t + 2) * kstep;
;             const char* a3 = a2 + kstep; const char* b3 = b2 + kstep;
;             if (last && has_next) S.a_ready(nxt);
;             if constexpr (SP2) {
;             PG8_LDB(B0, 0, 0); PG8_LDB(B1, 0, 1); PG8_SCHED; PG8_LDA(At, 0, 0); PG8_STAGE(PG8_SA(1, 1), a1 + hstep, voffA);
;             PG8_WAIT_V(8); PG8_WAIT_L(0); PG8_BAR; PG8_MMA(0, 0, At, B0); PG8_MMA(0, 1, At, B1); PG8_BAR; PG8_SCHED;
;             PG8_LDA(At, 0, 1); PG8_STAGE(PG8_SB(0, 0), b2, voffB); PG8_STAGE(PG8_SB(0, 1), b2 + hstep, voffB); PG8_STAGE(PG8_SA(0, 0), a2, voffA);
;             PG8_WAIT_V(8); PG8_WAIT_L(0); PG8_BAR; PG8_MMA(1, 0, At, B0); PG8_MMA(1, 1, At, B1); PG8_BAR; PG8_SCHED;
;             PG8_LDB(B0, 1, 0); PG8_LDB(B1, 1, 1); PG8_SCHED; PG8_LDA(At, 1, 0); PG8_STAGE(PG8_SA(0, 1), a2 + hstep, voffA);
;             PG8_WAIT_V(8); PG8_WAIT_L(0); PG8_BAR; PG8_MMA(0, 0, At, B0); PG8_MMA(0, 1, At, B1); PG8_BAR; PG8_SCHED;
;             PG8_LDA(At, 1, 1); PG8_STAGE(PG8_SB(1, 0), b3, voffB); PG8_STAGE(PG8_SB(1, 1), b3 + hstep, voffB); PG8_STAGE(PG8_SA(1, 0), a3, voffA);
;             PG8_WAIT_V(8); PG8_WAIT_L(0); PG8_BAR; PG8_MMA(1, 0, At, B0); PG8_MMA(1, 1, At, B1); PG8_BAR; PG8_SCHED;
	s_add_i32 s36, 0, 0x18000
	v_add_u32_e32 v140, s36, v137
	s_add_i32 s37, 0, 0x1c000
	ds_read_b128 v[150:153], v140
	ds_read_b128 v[154:157], v140 offset:1024
	ds_read_b128 v[162:165], v140 offset:2048
	ds_read_b128 v[166:169], v140 offset:3072
	v_add_u32_e32 v140, s37, v137
	ds_read_b128 v[174:177], v140
	ds_read_b128 v[178:181], v140 offset:1024
	ds_read_b128 v[182:185], v140 offset:2048
	ds_read_b128 v[186:189], v140 offset:3072
	s_add_u32 s28, s28, 0x160000
	s_addc_u32 s29, s29, 0
	s_mov_b32 m0, s34
	ds_read_b128 v[190:193], v160 offset:32768
	ds_read_b128 v[194:197], v160 offset:33792
	ds_read_b128 v[198:201], v160 offset:34816
	ds_read_b128 v[202:205], v160 offset:35840
	ds_read_b128 v[206:209], v160 offset:36864
	ds_read_b128 v[210:213], v160 offset:37888
	ds_read_b128 v[214:217], v160 offset:38912
	ds_read_b128 v[218:221], v160 offset:39936
	global_load_lds_dwordx4 v128, s[28:29]
	s_mov_b32 m0, s35
	s_nop 0
	global_load_lds_dwordx4 v132, s[28:29]
	s_waitcnt vmcnt(8)
	s_waitcnt lgkmcnt(0)
	s_barrier
	s_setprio 1
	s_waitcnt lgkmcnt(0)
	v_mfma_f32_16x16x32_bf16 v[124:127], v[150:153], v[190:193], v[124:127]
	v_mfma_f32_16x16x32_bf16 v[120:123], v[162:165], v[190:193], v[120:123]
	v_mfma_f32_16x16x32_bf16 v[116:119], v[150:153], v[198:201], v[116:119]
	v_mfma_f32_16x16x32_bf16 v[112:115], v[162:165], v[198:201], v[112:115]
	v_mfma_f32_16x16x32_bf16 v[108:111], v[150:153], v[206:209], v[108:111]
	v_mfma_f32_16x16x32_bf16 v[104:107], v[162:165], v[206:209], v[104:107]
	v_mfma_f32_16x16x32_bf16 v[100:103], v[150:153], v[214:217], v[100:103]
	v_mfma_f32_16x16x32_bf16 v[96:99], v[162:165], v[214:217], v[96:99]
	v_mfma_f32_16x16x32_bf16 v[124:127], v[154:157], v[194:197], v[124:127]
	v_mfma_f32_16x16x32_bf16 v[120:123], v[166:169], v[194:197], v[120:123]
	v_mfma_f32_16x16x32_bf16 v[116:119], v[154:157], v[202:205], v[116:119]
	v_mfma_f32_16x16x32_bf16 v[112:115], v[166:169], v[202:205], v[112:115]
	v_mfma_f32_16x16x32_bf16 v[108:111], v[154:157], v[210:213], v[108:111]
	v_mfma_f32_16x16x32_bf16 v[104:107], v[166:169], v[210:213], v[104:107]
	v_mfma_f32_16x16x32_bf16 v[100:103], v[154:157], v[218:221], v[100:103]
	v_mfma_f32_16x16x32_bf16 v[96:99], v[166:169], v[218:221], v[96:99]
	s_setprio 0
	s_setprio 1
	v_mfma_f32_16x16x32_bf16 v[60:63], v[174:177], v[190:193], v[60:63]
	v_mfma_f32_16x16x32_bf16 v[56:59], v[182:185], v[190:193], v[56:59]
	v_mfma_f32_16x16x32_bf16 v[52:55], v[174:177], v[198:201], v[52:55]
	v_mfma_f32_16x16x32_bf16 v[48:51], v[182:185], v[198:201], v[48:51]
	v_mfma_f32_16x16x32_bf16 v[44:47], v[174:177], v[206:209], v[44:47]
	v_mfma_f32_16x16x32_bf16 v[40:43], v[182:185], v[206:209], v[40:43]
	v_mfma_f32_16x16x32_bf16 v[36:39], v[174:177], v[214:217], v[36:39]
	v_mfma_f32_16x16x32_bf16 v[32:35], v[182:185], v[214:217], v[32:35]
	v_mfma_f32_16x16x32_bf16 v[60:63], v[178:181], v[194:197], v[60:63]
	v_mfma_f32_16x16x32_bf16 v[56:59], v[186:189], v[194:197], v[56:59]
	v_mfma_f32_16x16x32_bf16 v[52:55], v[178:181], v[202:205], v[52:55]
	v_mfma_f32_16x16x32_bf16 v[48:51], v[186:189], v[202:205], v[48:51]
	v_mfma_f32_16x16x32_bf16 v[44:47], v[178:181], v[210:213], v[44:47]
	v_mfma_f32_16x16x32_bf16 v[40:43], v[186:189], v[210:213], v[40:43]
	v_mfma_f32_16x16x32_bf16 v[36:39], v[178:181], v[218:221], v[36:39]
	v_mfma_f32_16x16x32_bf16 v[32:35], v[186:189], v[218:221], v[32:35]
	s_setprio 0
	s_barrier
	s_add_i32 s28, s36, s21
	s_add_i32 m0, s28, 0xffffff80
	ds_read_b128 v[190:193], v160 offset:49152
	ds_read_b128 v[194:197], v160 offset:50176
	ds_read_b128 v[198:201], v160 offset:51200
	ds_read_b128 v[202:205], v160 offset:52224
	ds_read_b128 v[206:209], v160 offset:53248
	ds_read_b128 v[210:213], v160 offset:54272
	ds_read_b128 v[214:217], v160 offset:55296
	ds_read_b128 v[218:221], v160 offset:56320
	global_load_lds_dwordx4 v130, s[26:27] offset:128
	s_add_i32 m0, s28, 0x1f80
	s_nop 0
	global_load_lds_dwordx4 v134, s[26:27] offset:128
	s_add_u32 s26, s26, 0x160080
	s_addc_u32 s27, s27, 0
	s_add_i32 s28, s37, s21
	s_mov_b32 m0, s28
	s_nop 0
	global_load_lds_dwordx4 v130, s[26:27]
	s_add_i32 m0, s28, 0x2000
	s_nop 0
	global_load_lds_dwordx4 v134, s[26:27]
	v_lshl_add_u64 v[222:223], v[226:227], 0, s[16:17]
	s_mov_b32 m0, s48
	s_nop 0
	global_load_lds_dwordx4 v[222:223], off
	v_lshl_add_u64 v[222:223], v[228:229], 0, s[16:17]
	s_mov_b32 m0, s49
	s_nop 0
	global_load_lds_dwordx4 v[222:223], off
	s_waitcnt vmcnt(8)
	s_waitcnt lgkmcnt(0)
	s_barrier
	s_setprio 1
	s_waitcnt lgkmcnt(0)
	v_mfma_f32_16x16x32_bf16 v[92:95], v[150:153], v[190:193], v[92:95]
	v_mfma_f32_16x16x32_bf16 v[88:91], v[162:165], v[190:193], v[88:91]
	v_mfma_f32_16x16x32_bf16 v[84:87], v[150:153], v[198:201], v[84:87]
	v_mfma_f32_16x16x32_bf16 v[80:83], v[162:165], v[198:201], v[80:83]
	v_mfma_f32_16x16x32_bf16 v[76:79], v[150:153], v[206:209], v[76:79]
	v_mfma_f32_16x16x32_bf16 v[72:75], v[162:165], v[206:209], v[72:75]
	v_mfma_f32_16x16x32_bf16 v[68:71], v[150:153], v[214:217], v[68:71]
	v_mfma_f32_16x16x32_bf16 v[64:67], v[162:165], v[214:217], v[64:67]
	v_mfma_f32_16x16x32_bf16 v[92:95], v[154:157], v[194:197], v[92:95]
	v_mfma_f32_16x16x32_bf16 v[88:91], v[166:169], v[194:197], v[88:91]
	v_mfma_f32_16x16x32_bf16 v[84:87], v[154:157], v[202:205], v[84:87]
	v_mfma_f32_16x16x32_bf16 v[80:83], v[166:169], v[202:205], v[80:83]
	v_mfma_f32_16x16x32_bf16 v[76:79], v[154:157], v[210:213], v[76:79]
	v_mfma_f32_16x16x32_bf16 v[72:75], v[166:169], v[210:213], v[72:75]
	v_mfma_f32_16x16x32_bf16 v[68:71], v[154:157], v[218:221], v[68:71]
	v_mfma_f32_16x16x32_bf16 v[64:67], v[166:169], v[218:221], v[64:67]
	s_setprio 0
	s_setprio 1
	v_mfma_f32_16x16x32_bf16 v[28:31], v[174:177], v[190:193], v[28:31]
	v_mfma_f32_16x16x32_bf16 v[24:27], v[182:185], v[190:193], v[24:27]
	v_mfma_f32_16x16x32_bf16 v[20:23], v[174:177], v[198:201], v[20:23]
	v_mfma_f32_16x16x32_bf16 v[16:19], v[182:185], v[198:201], v[16:19]
	v_mfma_f32_16x16x32_bf16 v[12:15], v[174:177], v[206:209], v[12:15]
	v_mfma_f32_16x16x32_bf16 v[8:11], v[182:185], v[206:209], v[8:11]
	v_mfma_f32_16x16x32_bf16 v[4:7], v[174:177], v[214:217], v[4:7]
	v_mfma_f32_16x16x32_bf16 v[0:3], v[182:185], v[214:217], v[0:3]
	v_mfma_f32_16x16x32_bf16 v[28:31], v[178:181], v[194:197], v[28:31]
	v_mfma_f32_16x16x32_bf16 v[24:27], v[186:189], v[194:197], v[24:27]
	v_mfma_f32_16x16x32_bf16 v[20:23], v[178:181], v[202:205], v[20:23]
	v_mfma_f32_16x16x32_bf16 v[16:19], v[186:189], v[202:205], v[16:19]
	v_mfma_f32_16x16x32_bf16 v[12:15], v[178:181], v[210:213], v[12:15]
	v_mfma_f32_16x16x32_bf16 v[8:11], v[186:189], v[210:213], v[8:11]
	v_mfma_f32_16x16x32_bf16 v[4:7], v[178:181], v[218:221], v[4:7]
	v_mfma_f32_16x16x32_bf16 v[0:3], v[186:189], v[218:221], v[0:3]
	s_setprio 0
	s_barrier
	s_add_i32 s73, s73, 2
	s_add_u32 s24, s24, 0x100
	s_addc_u32 s25, s25, 0
	s_add_u32 s67, s67, 0x100
	s_addc_u32 s72, s72, 0
	s_cmpk_gt_u32 s73, 0x55
	s_cbranch_scc0 .LBB0_606
	s_and_b64 vcc, exec, s[18:19]
	s_cbranch_vccz .LBB0_609
	s_barrier

; #define PG8_STAGE(bufoff, gbase, voff) do { _Pragma("unroll") for (int _i = 0; _i < 2; ++_i) \
;         __builtin_amdgcn_global_load_lds((const unsigned*)((const char*)(gbase) + (voff)[_i]), (PG8_LAS unsigned*)(lds + (bufoff) + ldsw + _i * 8192), 16, 0, 0); } while (0)
; #define PG8_LDA(dst, b, h) do { _Pragma("unroll") for (int m = 0; m < 4; ++m) _Pragma("unroll") for (int k = 0; k < 2; ++k) dst[m][k] = *(const PG8_LAS bf16x8*)(lds + PG8_SA(b, h) + aoff + m * 2048 + k * 1024); } while (0)
; #define PG8_LDB(dst, b, h) do { _Pragma("unroll") for (int n = 0; n < 2; ++n) _Pragma("unroll") for (int k = 0; k < 2; ++k) dst[n][k] = *(const PG8_LAS bf16x8*)(lds + PG8_SB(b, h) + boff + n * 2048 + k * 1024); } while (0)
; #define PG8_MMA(ai, bj, At, Bt) do { __builtin_amdgcn_s_setprio(1); _Pragma("unroll") for (int m = 0; m < 4; ++m) _Pragma("unroll") for (int n = 0; n < 2; ++n) _Pragma("unroll") for (int k = 0; k < 2; ++k) \
;         acc[ai][bj][m][n] = __builtin_amdgcn_mfma_f32_16x16x32_bf16(Bt[n][k], At[m][k], acc[ai][bj][m][n], 0, 0, 0); __builtin_amdgcn_s_setprio(0); } while (0)
; #define PG8_WAIT_V(n) asm volatile("s_waitcnt vmcnt(" #n ")" ::: "memory")
; #define PG8_WAIT_L(n) asm volatile("s_waitcnt lgkmcnt(" #n ")" ::: "memory")
; #define PG8_BAR __builtin_amdgcn_s_barrier()
; #define PG8_SCHED __builtin_amdgcn_sched_barrier(0)
; template <class Epi, class Sched, bool ALIGN_EPI = false, bool SP2 = false>
; __device__ __forceinline__ void gemm_phase(PG8_LAS unsigned char* lds, const Gemm g, const Sched& S, const Epi& E) {
;     ...
;             PG8_LDB(B0, 0, 0); PG8_LDB(B1, 0, 1); PG8_SCHED; PG8_LDA(At, 0, 0); PG8_STAGE(PG8_SA(1, 1), a1 + hstep, voffA);
;             PG8_WAIT_V(8); PG8_WAIT_L(0); PG8_BAR; PG8_MMA(0, 0, At, B0); PG8_MMA(0, 1, At, B1); PG8_BAR; PG8_SCHED;
;             PG8_LDA(At, 0, 1); PG8_STAGE(PG8_SB(0, 0), b2, voffB); PG8_STAGE(PG8_SB(0, 1), b2 + hstep, voffB); PG8_STAGE(PG8_SA(0, 0), a2, voffA);
;             PG8_WAIT_V(8); PG8_WAIT_L(0); PG8_BAR; PG8_MMA(1, 0, At, B0); PG8_MMA(1, 1, At, B1); PG8_BAR; PG8_SCHED;
.LBB0_744:
	ds_read_b128 v[112:115], v174
	ds_read_b128 v[116:119], v174 offset:1024
	ds_read_b128 v[158:161], v174 offset:2048
	ds_read_b128 v[162:165], v174 offset:3072
	ds_read_b128 v[166:169], v175
	ds_read_b128 v[178:181], v175 offset:1024
	ds_read_b128 v[182:185], v175 offset:2048
	ds_read_b128 v[186:189], v175 offset:3072
	s_add_u32 s36, s34, 0xfff80080
	s_addc_u32 s37, s35, -1
	s_cmp_eq_u32 s75, 28
	s_cselect_b32 s51, s25, s37
	s_cselect_b32 s50, s71, s36
	s_cselect_b32 s49, s23, s74
	s_cselect_b32 s48, s72, s73
	s_add_i32 m0, s31, 0xc000
	ds_read_b128 v[190:193], v176
	ds_read_b128 v[194:197], v176 offset:1024
	ds_read_b128 v[198:201], v176 offset:2048
	ds_read_b128 v[202:205], v176 offset:3072
	ds_read_b128 v[206:209], v176 offset:4096
	ds_read_b128 v[210:213], v176 offset:5120
	ds_read_b128 v[214:217], v176 offset:6144
	ds_read_b128 v[218:221], v176 offset:7168
	global_load_lds_dwordx4 v150, s[34:35]
	s_add_i32 m0, s31, 0xe000
	s_nop 0
	global_load_lds_dwordx4 v152, s[34:35]
	s_waitcnt vmcnt(8)
	s_waitcnt lgkmcnt(0)
	s_barrier
	s_setprio 1
	s_waitcnt lgkmcnt(0)
	v_mfma_f32_16x16x32_bf16 v[132:135], v[112:115], v[190:193], v[132:135]
	v_mfma_f32_16x16x32_bf16 v[128:131], v[158:161], v[190:193], v[128:131]
	v_mfma_f32_16x16x32_bf16 v[124:127], v[112:115], v[198:201], v[124:127]
	v_mfma_f32_16x16x32_bf16 v[120:123], v[158:161], v[198:201], v[120:123]
	v_mfma_f32_16x16x32_bf16 v[108:111], v[112:115], v[206:209], v[108:111]
	v_mfma_f32_16x16x32_bf16 v[104:107], v[158:161], v[206:209], v[104:107]
	v_mfma_f32_16x16x32_bf16 v[100:103], v[112:115], v[214:217], v[100:103]
	v_mfma_f32_16x16x32_bf16 v[96:99], v[158:161], v[214:217], v[96:99]
	v_mfma_f32_16x16x32_bf16 v[132:135], v[116:119], v[194:197], v[132:135]
	v_mfma_f32_16x16x32_bf16 v[128:131], v[162:165], v[194:197], v[128:131]
	v_mfma_f32_16x16x32_bf16 v[124:127], v[116:119], v[202:205], v[124:127]
	v_mfma_f32_16x16x32_bf16 v[120:123], v[162:165], v[202:205], v[120:123]
	v_mfma_f32_16x16x32_bf16 v[108:111], v[116:119], v[210:213], v[108:111]
	v_mfma_f32_16x16x32_bf16 v[104:107], v[162:165], v[210:213], v[104:107]
	v_mfma_f32_16x16x32_bf16 v[100:103], v[116:119], v[218:221], v[100:103]
	v_mfma_f32_16x16x32_bf16 v[96:99], v[162:165], v[218:221], v[96:99]
	s_setprio 0
	s_setprio 1
	v_mfma_f32_16x16x32_bf16 v[60:63], v[166:169], v[190:193], v[60:63]
	v_mfma_f32_16x16x32_bf16 v[56:59], v[182:185], v[190:193], v[56:59]
	v_mfma_f32_16x16x32_bf16 v[52:55], v[166:169], v[198:201], v[52:55]
	v_mfma_f32_16x16x32_bf16 v[48:51], v[182:185], v[198:201], v[48:51]
	v_mfma_f32_16x16x32_bf16 v[44:47], v[166:169], v[206:209], v[44:47]
	v_mfma_f32_16x16x32_bf16 v[40:43], v[182:185], v[206:209], v[40:43]
	v_mfma_f32_16x16x32_bf16 v[36:39], v[166:169], v[214:217], v[36:39]
	v_mfma_f32_16x16x32_bf16 v[32:35], v[182:185], v[214:217], v[32:35]
	v_mfma_f32_16x16x32_bf16 v[60:63], v[178:181], v[194:197], v[60:63]
	v_mfma_f32_16x16x32_bf16 v[56:59], v[186:189], v[194:197], v[56:59]
	v_mfma_f32_16x16x32_bf16 v[52:55], v[178:181], v[202:205], v[52:55]
	v_mfma_f32_16x16x32_bf16 v[48:51], v[186:189], v[202:205], v[48:51]
	v_mfma_f32_16x16x32_bf16 v[44:47], v[178:181], v[210:213], v[44:47]
	v_mfma_f32_16x16x32_bf16 v[40:43], v[186:189], v[210:213], v[40:43]
	v_mfma_f32_16x16x32_bf16 v[36:39], v[178:181], v[218:221], v[36:39]
	v_mfma_f32_16x16x32_bf16 v[32:35], v[186:189], v[218:221], v[32:35]
	s_setprio 0
	s_barrier
	s_add_i32 s36, s66, s21
	s_mov_b32 m0, s36
	ds_read_b128 v[190:193], v176 offset:16384
	ds_read_b128 v[194:197], v176 offset:17408
	ds_read_b128 v[198:201], v176 offset:18432
	ds_read_b128 v[202:205], v176 offset:19456
	ds_read_b128 v[206:209], v176 offset:20480
	ds_read_b128 v[210:213], v176 offset:21504
	ds_read_b128 v[214:217], v176 offset:22528
	ds_read_b128 v[218:221], v176 offset:23552
	global_load_lds_dwordx4 v142, s[48:49]
	s_add_i32 m0, s36, 0x2000
	s_add_u32 s36, s48, 0x80000
	s_addc_u32 s37, s49, 0
	s_add_i32 s58, s67, s21
	global_load_lds_dwordx4 v146, s[48:49]
	s_mov_b32 m0, s58
	global_load_lds_dwordx4 v142, s[36:37]
	s_add_i32 m0, s58, 0x2000
	s_nop 0
	global_load_lds_dwordx4 v146, s[36:37]
	s_mov_b32 m0, s31
	s_nop 0
	global_load_lds_dwordx4 v140, s[50:51]
	s_mov_b32 m0, s39
	s_nop 0
	global_load_lds_dwordx4 v144, s[50:51]
	s_waitcnt vmcnt(8)
	s_waitcnt lgkmcnt(0)
	s_barrier
	s_setprio 1
	s_waitcnt lgkmcnt(0)
	v_mfma_f32_16x16x32_bf16 v[92:95], v[112:115], v[190:193], v[92:95]
	v_mfma_f32_16x16x32_bf16 v[88:91], v[158:161], v[190:193], v[88:91]
	v_mfma_f32_16x16x32_bf16 v[84:87], v[112:115], v[198:201], v[84:87]
	v_mfma_f32_16x16x32_bf16 v[80:83], v[158:161], v[198:201], v[80:83]
	v_mfma_f32_16x16x32_bf16 v[76:79], v[112:115], v[206:209], v[76:79]
	v_mfma_f32_16x16x32_bf16 v[72:75], v[158:161], v[206:209], v[72:75]
	v_mfma_f32_16x16x32_bf16 v[68:71], v[112:115], v[214:217], v[68:71]
	v_mfma_f32_16x16x32_bf16 v[64:67], v[158:161], v[214:217], v[64:67]
	v_mfma_f32_16x16x32_bf16 v[92:95], v[116:119], v[194:197], v[92:95]
	v_mfma_f32_16x16x32_bf16 v[88:91], v[162:165], v[194:197], v[88:91]
	v_mfma_f32_16x16x32_bf16 v[84:87], v[116:119], v[202:205], v[84:87]
	v_mfma_f32_16x16x32_bf16 v[80:83], v[162:165], v[202:205], v[80:83]
	v_mfma_f32_16x16x32_bf16 v[76:79], v[116:119], v[210:213], v[76:79]
	v_mfma_f32_16x16x32_bf16 v[72:75], v[162:165], v[210:213], v[72:75]
	v_mfma_f32_16x16x32_bf16 v[68:71], v[116:119], v[218:221], v[68:71]
	v_mfma_f32_16x16x32_bf16 v[64:67], v[162:165], v[218:221], v[64:67]
	s_setprio 0
	s_setprio 1
	v_mfma_f32_16x16x32_bf16 v[28:31], v[166:169], v[190:193], v[28:31]
	v_mfma_f32_16x16x32_bf16 v[24:27], v[182:185], v[190:193], v[24:27]
	v_mfma_f32_16x16x32_bf16 v[20:23], v[166:169], v[198:201], v[20:23]
	v_mfma_f32_16x16x32_bf16 v[16:19], v[182:185], v[198:201], v[16:19]
	v_mfma_f32_16x16x32_bf16 v[12:15], v[166:169], v[206:209], v[12:15]
	v_mfma_f32_16x16x32_bf16 v[8:11], v[182:185], v[206:209], v[8:11]
	v_mfma_f32_16x16x32_bf16 v[4:7], v[166:169], v[214:217], v[4:7]
	v_mfma_f32_16x16x32_bf16 v[0:3], v[182:185], v[214:217], v[0:3]
	v_mfma_f32_16x16x32_bf16 v[28:31], v[178:181], v[194:197], v[28:31]
	v_mfma_f32_16x16x32_bf16 v[24:27], v[186:189], v[194:197], v[24:27]
	v_mfma_f32_16x16x32_bf16 v[20:23], v[178:181], v[202:205], v[20:23]
	v_mfma_f32_16x16x32_bf16 v[16:19], v[186:189], v[202:205], v[16:19]
	v_mfma_f32_16x16x32_bf16 v[12:15], v[178:181], v[210:213], v[12:15]
	v_mfma_f32_16x16x32_bf16 v[8:11], v[186:189], v[210:213], v[8:11]
	v_mfma_f32_16x16x32_bf16 v[4:7], v[178:181], v[218:221], v[4:7]
	v_mfma_f32_16x16x32_bf16 v[0:3], v[186:189], v[218:221], v[0:3]
	s_setprio 0
	s_barrier
; #define PG8_STAGE(bufoff, gbase, voff) do { _Pragma("unroll") for (int _i = 0; _i < 2; ++_i) \
;         __builtin_amdgcn_global_load_lds((const unsigned*)((const char*)(gbase) + (voff)[_i]), (PG8_LAS unsigned*)(lds + (bufoff) + ldsw + _i * 8192), 16, 0, 0); } while (0)
; #define PG8_LDA(dst, b, h) do { _Pragma("unroll") for (int m = 0; m < 4; ++m) _Pragma("unroll") for (int k = 0; k < 2; ++k) dst[m][k] = *(const PG8_LAS bf16x8*)(lds + PG8_SA(b, h) + aoff + m * 2048 + k * 1024); } while (0)
; #define PG8_LDB(dst, b, h) do { _Pragma("unroll") for (int n = 0; n < 2; ++n) _Pragma("unroll") for (int k = 0; k < 2; ++k) dst[n][k] = *(const PG8_LAS bf16x8*)(lds + PG8_SB(b, h) + boff + n * 2048 + k * 1024); } while (0)
; template <class Epi, class Sched, bool ALIGN_EPI = false, bool SP2 = false>
; __device__ __forceinline__ void gemm_phase(PG8_LAS unsigned char* lds, const Gemm g, const Sched& S, const Epi& E) {
;     ...
;         for (int t = 0; t < nt; t += 2) {
;             const bool last = (t == nt - 2);
;             const char* a1 = cA + (size_t)(t + 1) * kstep;
;             const char* a2 = last ? nA : cA + (size_t)(t + 2) * kstep; const char* b2 = last ? nB : cB + (size_t)(t + 2) * kstep;
;             const char* a3 = a2 + kstep; const char* b3 = b2 + kstep;
;             if (last && has_next) S.a_ready(nxt);
;             if constexpr (SP2) {
;             PG8_LDB(B0, 0, 0); PG8_LDB(B1, 0, 1); PG8_SCHED; PG8_LDA(At, 0, 0); PG8_STAGE(PG8_SA(1, 1), a1 + hstep, voffA);
;             PG8_WAIT_V(8); PG8_WAIT_L(0); PG8_BAR; PG8_MMA(0, 0, At, B0); PG8_MMA(0, 1, At, B1); PG8_BAR; PG8_SCHED;
;             PG8_LDA(At, 0, 1); PG8_STAGE(PG8_SB(0, 0), b2, voffB); PG8_STAGE(PG8_SB(0, 1), b2 + hstep, voffB); PG8_STAGE(PG8_SA(0, 0), a2, voffA);
;             PG8_WAIT_V(8); PG8_WAIT_L(0); PG8_BAR; PG8_MMA(1, 0, At, B0); PG8_MMA(1, 1, At, B1); PG8_BAR; PG8_SCHED;
;             PG8_LDB(B0, 1, 0); PG8_LDB(B1, 1, 1); PG8_SCHED; PG8_LDA(At, 1, 0); PG8_STAGE(PG8_SA(0, 1), a2 + hstep, voffA);
;             PG8_WAIT_V(8); PG8_WAIT_L(0); PG8_BAR; PG8_MMA(0, 0, At, B0); PG8_MMA(0, 1, At, B1); PG8_BAR; PG8_SCHED;
;             PG8_LDA(At, 1, 1); PG8_STAGE(PG8_SB(1, 0), b3, voffB); PG8_STAGE(PG8_SB(1, 1), b3 + hstep, voffB); PG8_STAGE(PG8_SA(1, 0), a3, voffA);
;             PG8_WAIT_V(8); PG8_WAIT_L(0); PG8_BAR; PG8_MMA(1, 0, At, B0); PG8_MMA(1, 1, At, B1); PG8_BAR; PG8_SCHED;
	s_add_i32 s58, 0, 0x18000
	v_add_u32_e32 v148, s58, v137
	s_add_i32 s59, 0, 0x1c000
	ds_read_b128 v[112:115], v148
	ds_read_b128 v[116:119], v148 offset:1024
	ds_read_b128 v[158:161], v148 offset:2048
	ds_read_b128 v[162:165], v148 offset:3072
	v_add_u32_e32 v148, s59, v137
	ds_read_b128 v[166:169], v148
	ds_read_b128 v[178:181], v148 offset:1024
	ds_read_b128 v[182:185], v148 offset:2048
	ds_read_b128 v[186:189], v148 offset:3072
	s_add_u32 s36, s50, 0x80000
	s_addc_u32 s37, s51, 0
	s_mov_b32 m0, s52
	ds_read_b128 v[190:193], v176 offset:32768
	ds_read_b128 v[194:197], v176 offset:33792
	ds_read_b128 v[198:201], v176 offset:34816
	ds_read_b128 v[202:205], v176 offset:35840
	ds_read_b128 v[206:209], v176 offset:36864
	ds_read_b128 v[210:213], v176 offset:37888
	ds_read_b128 v[214:217], v176 offset:38912
	ds_read_b128 v[218:221], v176 offset:39936
	global_load_lds_dwordx4 v140, s[36:37]
	s_mov_b32 m0, s53
	s_nop 0
	global_load_lds_dwordx4 v144, s[36:37]
	s_waitcnt vmcnt(8)
	s_waitcnt lgkmcnt(0)
	s_barrier
	s_setprio 1
	s_waitcnt lgkmcnt(0)
	v_mfma_f32_16x16x32_bf16 v[132:135], v[112:115], v[190:193], v[132:135]
	v_mfma_f32_16x16x32_bf16 v[128:131], v[158:161], v[190:193], v[128:131]
	v_mfma_f32_16x16x32_bf16 v[124:127], v[112:115], v[198:201], v[124:127]
	v_mfma_f32_16x16x32_bf16 v[120:123], v[158:161], v[198:201], v[120:123]
	v_mfma_f32_16x16x32_bf16 v[108:111], v[112:115], v[206:209], v[108:111]
	v_mfma_f32_16x16x32_bf16 v[104:107], v[158:161], v[206:209], v[104:107]
	v_mfma_f32_16x16x32_bf16 v[100:103], v[112:115], v[214:217], v[100:103]
	v_mfma_f32_16x16x32_bf16 v[96:99], v[158:161], v[214:217], v[96:99]
	v_mfma_f32_16x16x32_bf16 v[132:135], v[116:119], v[194:197], v[132:135]
	v_mfma_f32_16x16x32_bf16 v[128:131], v[162:165], v[194:197], v[128:131]
	v_mfma_f32_16x16x32_bf16 v[124:127], v[116:119], v[202:205], v[124:127]
	v_mfma_f32_16x16x32_bf16 v[120:123], v[162:165], v[202:205], v[120:123]
	v_mfma_f32_16x16x32_bf16 v[108:111], v[116:119], v[210:213], v[108:111]
	v_mfma_f32_16x16x32_bf16 v[104:107], v[162:165], v[210:213], v[104:107]
	v_mfma_f32_16x16x32_bf16 v[100:103], v[116:119], v[218:221], v[100:103]
	v_mfma_f32_16x16x32_bf16 v[96:99], v[162:165], v[218:221], v[96:99]
	s_setprio 0
	s_setprio 1
	v_mfma_f32_16x16x32_bf16 v[60:63], v[166:169], v[190:193], v[60:63]
	v_mfma_f32_16x16x32_bf16 v[56:59], v[182:185], v[190:193], v[56:59]
	v_mfma_f32_16x16x32_bf16 v[52:55], v[166:169], v[198:201], v[52:55]
	v_mfma_f32_16x16x32_bf16 v[48:51], v[182:185], v[198:201], v[48:51]
	v_mfma_f32_16x16x32_bf16 v[44:47], v[166:169], v[206:209], v[44:47]
	v_mfma_f32_16x16x32_bf16 v[40:43], v[182:185], v[206:209], v[40:43]
	v_mfma_f32_16x16x32_bf16 v[36:39], v[166:169], v[214:217], v[36:39]
	v_mfma_f32_16x16x32_bf16 v[32:35], v[182:185], v[214:217], v[32:35]
	v_mfma_f32_16x16x32_bf16 v[60:63], v[178:181], v[194:197], v[60:63]
	v_mfma_f32_16x16x32_bf16 v[56:59], v[186:189], v[194:197], v[56:59]
	v_mfma_f32_16x16x32_bf16 v[52:55], v[178:181], v[202:205], v[52:55]
	v_mfma_f32_16x16x32_bf16 v[48:51], v[186:189], v[202:205], v[48:51]
	v_mfma_f32_16x16x32_bf16 v[44:47], v[178:181], v[210:213], v[44:47]
	v_mfma_f32_16x16x32_bf16 v[40:43], v[186:189], v[210:213], v[40:43]
	v_mfma_f32_16x16x32_bf16 v[36:39], v[178:181], v[218:221], v[36:39]
	v_mfma_f32_16x16x32_bf16 v[32:35], v[186:189], v[218:221], v[32:35]
	s_setprio 0
	s_barrier
	s_add_i32 s36, s58, s21
	s_add_i32 m0, s36, 0xffffff80
	ds_read_b128 v[190:193], v176 offset:49152
	ds_read_b128 v[194:197], v176 offset:50176
	ds_read_b128 v[198:201], v176 offset:51200
	ds_read_b128 v[202:205], v176 offset:52224
	ds_read_b128 v[206:209], v176 offset:53248
	ds_read_b128 v[210:213], v176 offset:54272
	ds_read_b128 v[214:217], v176 offset:55296
	ds_read_b128 v[218:221], v176 offset:56320
	global_load_lds_dwordx4 v142, s[48:49] offset:128
	s_add_i32 m0, s36, 0x1f80
	s_nop 0
	global_load_lds_dwordx4 v146, s[48:49] offset:128
	s_add_u32 s36, s48, 0x80080
	s_addc_u32 s37, s49, 0
	s_add_i32 s48, s59, s21
	s_mov_b32 m0, s48
	s_nop 0
	global_load_lds_dwordx4 v142, s[36:37]
	s_add_i32 m0, s48, 0x2000
	s_nop 0
	global_load_lds_dwordx4 v146, s[36:37]
	s_add_i32 m0, s55, 0xffffff80
	s_nop 0
	global_load_lds_dwordx4 v140, s[50:51] offset:128
	s_add_i32 m0, s57, 0xffffff80
	s_nop 0
	global_load_lds_dwordx4 v144, s[50:51] offset:128
	s_waitcnt vmcnt(8)
	s_waitcnt lgkmcnt(0)
	s_barrier
	s_setprio 1
	s_waitcnt lgkmcnt(0)
	v_mfma_f32_16x16x32_bf16 v[92:95], v[112:115], v[190:193], v[92:95]
	v_mfma_f32_16x16x32_bf16 v[88:91], v[158:161], v[190:193], v[88:91]
	v_mfma_f32_16x16x32_bf16 v[84:87], v[112:115], v[198:201], v[84:87]
	v_mfma_f32_16x16x32_bf16 v[80:83], v[158:161], v[198:201], v[80:83]
	v_mfma_f32_16x16x32_bf16 v[76:79], v[112:115], v[206:209], v[76:79]
	v_mfma_f32_16x16x32_bf16 v[72:75], v[158:161], v[206:209], v[72:75]
	v_mfma_f32_16x16x32_bf16 v[68:71], v[112:115], v[214:217], v[68:71]
	v_mfma_f32_16x16x32_bf16 v[64:67], v[158:161], v[214:217], v[64:67]
	v_mfma_f32_16x16x32_bf16 v[92:95], v[116:119], v[194:197], v[92:95]
	v_mfma_f32_16x16x32_bf16 v[88:91], v[162:165], v[194:197], v[88:91]
	v_mfma_f32_16x16x32_bf16 v[84:87], v[116:119], v[202:205], v[84:87]
	v_mfma_f32_16x16x32_bf16 v[80:83], v[162:165], v[202:205], v[80:83]
	v_mfma_f32_16x16x32_bf16 v[76:79], v[116:119], v[210:213], v[76:79]
	v_mfma_f32_16x16x32_bf16 v[72:75], v[162:165], v[210:213], v[72:75]
	v_mfma_f32_16x16x32_bf16 v[68:71], v[116:119], v[218:221], v[68:71]
	v_mfma_f32_16x16x32_bf16 v[64:67], v[162:165], v[218:221], v[64:67]
	s_setprio 0
	s_setprio 1
	v_mfma_f32_16x16x32_bf16 v[28:31], v[166:169], v[190:193], v[28:31]
	v_mfma_f32_16x16x32_bf16 v[24:27], v[182:185], v[190:193], v[24:27]
	v_mfma_f32_16x16x32_bf16 v[20:23], v[166:169], v[198:201], v[20:23]
	v_mfma_f32_16x16x32_bf16 v[16:19], v[182:185], v[198:201], v[16:19]
	v_mfma_f32_16x16x32_bf16 v[12:15], v[166:169], v[206:209], v[12:15]
	v_mfma_f32_16x16x32_bf16 v[8:11], v[182:185], v[206:209], v[8:11]
	v_mfma_f32_16x16x32_bf16 v[4:7], v[166:169], v[214:217], v[4:7]
	v_mfma_f32_16x16x32_bf16 v[0:3], v[182:185], v[214:217], v[0:3]
	v_mfma_f32_16x16x32_bf16 v[28:31], v[178:181], v[194:197], v[28:31]
	v_mfma_f32_16x16x32_bf16 v[24:27], v[186:189], v[194:197], v[24:27]
	v_mfma_f32_16x16x32_bf16 v[20:23], v[178:181], v[202:205], v[20:23]
	v_mfma_f32_16x16x32_bf16 v[16:19], v[186:189], v[202:205], v[16:19]
	v_mfma_f32_16x16x32_bf16 v[12:15], v[178:181], v[210:213], v[12:15]
	v_mfma_f32_16x16x32_bf16 v[8:11], v[186:189], v[210:213], v[8:11]
	v_mfma_f32_16x16x32_bf16 v[4:7], v[178:181], v[218:221], v[4:7]
	v_mfma_f32_16x16x32_bf16 v[0:3], v[186:189], v[218:221], v[0:3]
	s_setprio 0
	s_barrier
	s_add_i32 s75, s75, 2
	s_add_u32 s34, s34, 0x100
	s_addc_u32 s35, s35, 0
	s_add_u32 s73, s73, 0x100
	s_addc_u32 s74, s74, 0
	s_cmp_gt_u32 s75, 29
	s_cbranch_scc0 .LBB0_744
	s_and_b64 vcc, exec, s[18:19]
	s_cbranch_vccz .LBB0_747
	s_barrier
